# variant of v32: movable end-of-tile exps spread one per MFMA gap over PV groups 1-2 instead of two per gap in group 2
# speedup vs baseline: 1.0052x; 1.0052x over previous
; __device__ __forceinline__ void finishSM(f32x16& p0, f32x16& p1, float alpha, float& l_reg, bf16x8& pa0, bf16x8& pa1, bf16x8& pa2, bf16x8& pa3) {
;   for (int r = 0; r < 16; ++r) p1[r] = __builtin_amdgcn_exp2f(p1[r]);
;   float ps = 0; for (int r = 0; r < 16; ++r) ps += p0[r]; for (int r = 0; r < 16; ++r) ps += p1[r];
;   { auto rr = __builtin_amdgcn_permlane32_swap(__float_as_uint(ps), __float_as_uint(ps), false, false);
;     ps = __uint_as_float(rr[0]) + __uint_as_float(rr[1]); }
;   l_reg = l_reg * alpha + ps;
;     ...
;   PK4(p0, 0, pa0); PK4(p0, 8, pa1); PK4(p1, 0, pa2); PK4(p1, 8, pa3);
;     ...
; }
.LBB0_352:
	s_waitcnt lgkmcnt(0)
	s_barrier
	ds_read_b128 v[80:83], v207 offset:16384
	ds_read_b128 v[84:87], v207 offset:24576
	ds_read_b128 v[162:165], v208 offset:16384
	ds_read_b128 v[166:169], v208 offset:24576
	v_exp_f32_e32 v170, v72
	v_exp_f32_e32 v171, v73
	v_exp_f32_e32 v172, v74
	v_exp_f32_e32 v173, v75
	v_exp_f32_e32 v174, v76
	v_exp_f32_e32 v175, v77
	v_exp_f32_e32 v176, v78
	v_exp_f32_e32 v79, v79
	s_waitcnt lgkmcnt(3)
	v_mfma_f32_32x32x16_bf16 v[96:111], v[80:83], v[142:145], 0
	v_exp_f32_e32 v236, v64
	v_add_f32_e32 v64, 0, v229
	v_add_f32_e32 v64, v243, v64
	v_add_f32_e32 v64, v244, v64
	s_waitcnt lgkmcnt(2)
	v_mfma_f32_32x32x16_bf16 v[80:95], v[84:87], v[142:145], 0
	v_add_f32_e32 v64, v246, v64
	v_add_f32_e32 v64, v242, v64
	v_add_f32_e32 v64, v245, v64
	s_waitcnt lgkmcnt(1)
	v_mfma_f32_32x32x16_bf16 v[96:111], v[162:165], v[138:141], v[96:111]
	v_add_f32_e32 v64, v227, v64
	v_add_f32_e32 v64, v228, v64
	v_add_f32_e32 v64, v223, v64
	s_waitcnt lgkmcnt(0)
	v_mfma_f32_32x32x16_bf16 v[80:95], v[166:169], v[138:141], v[80:95]
	ds_read_b128 v[162:165], v209 offset:16384
	ds_read_b128 v[166:169], v209 offset:24576
	v_add_f32_e32 v64, v226, v64
	v_add_f32_e32 v64, v224, v64
	v_add_f32_e32 v64, v225, v64
	v_add_f32_e32 v64, v220, v64
	v_exp_f32_e32 v237, v65
	s_waitcnt lgkmcnt(1)
	v_mfma_f32_32x32x16_bf16 v[96:111], v[162:165], v[112:115], v[96:111]
	v_add_f32_e32 v64, v222, v64
	v_exp_f32_e32 v238, v66
	v_add_f32_e32 v64, v219, v64
	v_exp_f32_e32 v239, v67
	s_waitcnt lgkmcnt(0)
	v_mfma_f32_32x32x16_bf16 v[80:95], v[166:169], v[112:115], v[80:95]
	ds_read_b128 v[162:165], v210 offset:16384
	ds_read_b128 v[166:169], v210 offset:24576
	v_add_f32_e32 v64, v221, v64
	v_exp_f32_e32 v247, v68
	v_add_f32_e32 v64, v236, v64
	v_exp_f32_e32 v248, v69
	s_waitcnt lgkmcnt(1)
	v_mfma_f32_32x32x16_bf16 v[96:111], v[162:165], v[116:119], v[96:111]
	v_add_f32_e32 v64, v237, v64
	v_exp_f32_e32 v249, v70
	v_add_f32_e32 v64, v238, v64
	v_exp_f32_e32 v252, v71
	s_waitcnt lgkmcnt(0)
	v_mfma_f32_32x32x16_bf16 v[80:95], v[166:169], v[116:119], v[80:95]
	ds_read_b128 v[162:165], v190 offset:16384
	ds_read_b128 v[166:169], v190 offset:24576
	v_add_f32_e32 v64, v239, v64
	v_add_f32_e32 v64, v247, v64
	v_add_f32_e32 v64, v248, v64
	v_add_f32_e32 v64, v249, v64
	v_add_f32_e32 v64, v252, v64
	v_add_f32_e32 v64, v170, v64
	s_waitcnt lgkmcnt(1)
	v_mfma_f32_32x32x16_bf16 v[96:111], v[162:165], v[120:123], v[96:111]
	v_add_f32_e32 v64, v171, v64
	v_add_f32_e32 v64, v172, v64
	v_add_f32_e32 v64, v173, v64
	v_add_f32_e32 v64, v174, v64
	v_add_f32_e32 v64, v175, v64
	s_waitcnt lgkmcnt(0)
	v_mfma_f32_32x32x16_bf16 v[80:95], v[166:169], v[120:123], v[80:95]
	ds_read_b128 v[162:165], v191 offset:16384
	ds_read_b128 v[166:169], v191 offset:24576
	v_add_f32_e32 v64, v176, v64
	v_add_f32_e32 v64, v79, v64
	v_mov_b32_e32 v65, v64
	s_nop 1
	v_permlane32_swap_b32_e32 v64, v65
	v_add_f32_e32 v64, v64, v65
	s_waitcnt lgkmcnt(1)
	v_mfma_f32_32x32x16_bf16 v[96:111], v[162:165], v[124:127], v[96:111]
	v_add_f32_e32 v128, v215, v64
	v_cvt_pk_bf16_f32 v64, v229, v243
	v_cvt_pk_bf16_f32 v65, v244, v246
	v_cvt_pk_bf16_f32 v66, v242, v245
	v_cvt_pk_bf16_f32 v67, v227, v228
	s_waitcnt lgkmcnt(0)
	v_mfma_f32_32x32x16_bf16 v[80:95], v[166:169], v[124:127], v[80:95]
	ds_read_b128 v[162:165], v192 offset:16384
	ds_read_b128 v[166:169], v192 offset:24576
	v_cvt_pk_bf16_f32 v68, v223, v226
	v_cvt_pk_bf16_f32 v69, v224, v225
	v_cvt_pk_bf16_f32 v70, v220, v222
	v_cvt_pk_bf16_f32 v71, v219, v221
	v_cvt_pk_bf16_f32 v72, v236, v237
	v_cvt_pk_bf16_f32 v73, v238, v239
	s_waitcnt lgkmcnt(1)
	v_mfma_f32_32x32x16_bf16 v[96:111], v[162:165], v[130:133], v[96:111]
	v_cvt_pk_bf16_f32 v74, v247, v248
	v_cvt_pk_bf16_f32 v75, v249, v252
	v_cvt_pk_bf16_f32 v76, v170, v171
	v_cvt_pk_bf16_f32 v77, v172, v173
	v_cvt_pk_bf16_f32 v78, v174, v175
	s_waitcnt lgkmcnt(0)
	v_mfma_f32_32x32x16_bf16 v[80:95], v[166:169], v[130:133], v[80:95]
	ds_read_b128 v[162:165], v193 offset:16384
	ds_read_b128 v[166:169], v193 offset:24576
	ds_read_b64_tr_b16 v[180:181], v206 offset:0
	ds_read_b64_tr_b16 v[182:183], v206 offset:0x800
	ds_read_b64_tr_b16 v[184:185], v206 offset:0x1000
	ds_read_b64_tr_b16 v[186:187], v206 offset:0x1800
	ds_read_b64_tr_b16 v[216:217], v206 offset:0x2000
	ds_read_b64_tr_b16 v[218:219], v206 offset:0x2800
	ds_read_b64_tr_b16 v[220:221], v206 offset:0x3000
	ds_read_b64_tr_b16 v[222:223], v206 offset:0x3800
	v_cvt_pk_bf16_f32 v79, v176, v79
	s_nop 0
	v_permlane32_swap_b32_e32 v64, v66
	v_permlane32_swap_b32_e32 v65, v67
	v_permlane32_swap_b32_e32 v68, v70
	v_permlane32_swap_b32_e32 v69, v71
	s_waitcnt lgkmcnt(9)
	v_mfma_f32_32x32x16_bf16 v[96:111], v[162:165], v[134:137], v[96:111]
	v_permlane32_swap_b32_e32 v72, v74
	v_permlane32_swap_b32_e32 v73, v75
	v_permlane32_swap_b32_e32 v76, v78
	v_permlane32_swap_b32_e32 v77, v79
	s_waitcnt lgkmcnt(8)
	v_mfma_f32_32x32x16_bf16 v[80:95], v[166:169], v[134:137], v[80:95]
	s_waitcnt vmcnt(0)
	ds_write_b128 v211, v[146:149] offset:32768
	s_nop 0
	s_waitcnt lgkmcnt(7)
	v_mfma_f32_32x32x16_bf16 v[0:15], v[64:67], v[180:183], v[0:15]
	ds_read_b64_tr_b16 v[180:181], v206 offset:0x200
	ds_read_b64_tr_b16 v[182:183], v206 offset:0xa00
	v_add_co_u32_e32 v166, vcc, s19, v178
	s_nop 1
	v_addc_co_u32_e32 v167, vcc, -1, v179, vcc
	v_add_co_u32_e32 v170, vcc, s20, v178
	s_nop 1
	v_addc_co_u32_e32 v171, vcc, -1, v179, vcc
	s_waitcnt lgkmcnt(7)
	v_mfma_f32_32x32x16_bf16 v[0:15], v[68:71], v[184:187], v[0:15]
	ds_read_b64_tr_b16 v[184:185], v206 offset:0x1200
	ds_read_b64_tr_b16 v[186:187], v206 offset:0x1a00
	global_load_dwordx4 v[162:165], v[166:167], off
	s_nop 0
	global_load_dwordx4 v[166:169], v[166:167], off offset:-512
	s_nop 0
	global_load_dwordx4 v[174:177], v[170:171], off
	s_nop 0
	global_load_dwordx4 v[170:173], v[170:171], off offset:-512
	s_waitcnt lgkmcnt(7)
; #define SBAR() __builtin_amdgcn_sched_barrier(0)
; template <int D0, int BOFF> __device__ __forceinline__ void pv_one_i(f32x16& od, int vb, bf16x8 pa0, bf16x8 pa1, bf16x8 pa2, bf16x8 pa3) {
;   const s16x4 l0 = tr_read<BOFF + v_rd_off(D0, 0, 0)>(vb), h0 = tr_read<BOFF + v_rd_off(D0, 0, 1)>(vb), l1 = tr_read<BOFF + v_rd_off(D0, 1, 0)>(vb), h1 = tr_read<BOFF + v_rd_off(D0, 1, 1)>(vb);
;   const s16x4 l2 = tr_read<BOFF + v_rd_off(D0, 2, 0)>(vb), h2 = tr_read<BOFF + v_rd_off(D0, 2, 1)>(vb), l3 = tr_read<BOFF + v_rd_off(D0, 3, 0)>(vb), h3 = tr_read<BOFF + v_rd_off(D0, 3, 1)>(vb);
;   asm volatile("s_waitcnt lgkmcnt(0)" ::: "memory"); SBAR();
;     ...
;   od = __builtin_amdgcn_mfma_f32_32x32x16_bf16(pa0, PK(l0, h0), od, 0, 0, 0);
;   od = __builtin_amdgcn_mfma_f32_32x32x16_bf16(pa1, PK(l1, h1), od, 0, 0, 0);
;   od = __builtin_amdgcn_mfma_f32_32x32x16_bf16(pa2, PK(l2, h2), od, 0, 0, 0);
;   od = __builtin_amdgcn_mfma_f32_32x32x16_bf16(pa3, PK(l3, h3), od, 0, 0, 0);
;     ...
; }
; template <int BOFF> __device__ __forceinline__ void pv_i(f32x16* o, int vb, bf16x8 pa0, bf16x8 pa1, bf16x8 pa2, bf16x8 pa3) {
;   pv_one_i<0, BOFF>(o[0], vb, pa0, pa1, pa2, pa3); pv_one_i<1, BOFF>(o[1], vb, pa0, pa1, pa2, pa3); pv_one_i<2, BOFF>(o[2], vb, pa0, pa1, pa2, pa3); pv_one_i<3, BOFF>(o[3], vb, pa0, pa1, pa2, pa3);
; }
	v_mfma_f32_32x32x16_bf16 v[0:15], v[72:75], v[216:219], v[0:15]
	ds_read_b64_tr_b16 v[216:217], v206 offset:0x2200
	ds_read_b64_tr_b16 v[218:219], v206 offset:0x2a00
	s_waitcnt lgkmcnt(7)
	v_mfma_f32_32x32x16_bf16 v[0:15], v[76:79], v[220:223], v[0:15]
	ds_read_b64_tr_b16 v[220:221], v206 offset:0x3200
	ds_read_b64_tr_b16 v[222:223], v206 offset:0x3a00
	ds_write_b128 v212, v[150:153] offset:32768
	s_waitcnt lgkmcnt(7)
	v_mfma_f32_32x32x16_bf16 v[16:31], v[64:67], v[180:183], v[16:31]
	ds_read_b64_tr_b16 v[180:181], v206 offset:0x400
	ds_read_b64_tr_b16 v[182:183], v206 offset:0xc00
	v_exp_f32_e32 v215, v108
	s_waitcnt lgkmcnt(7)
	v_mfma_f32_32x32x16_bf16 v[16:31], v[68:71], v[184:187], v[16:31]
	ds_read_b64_tr_b16 v[184:185], v206 offset:0x1400
	ds_read_b64_tr_b16 v[186:187], v206 offset:0x1c00
	v_exp_f32_e32 v188, v102
	s_waitcnt lgkmcnt(7)
	v_mfma_f32_32x32x16_bf16 v[16:31], v[72:75], v[216:219], v[16:31]
	ds_read_b64_tr_b16 v[216:217], v206 offset:0x2400
	ds_read_b64_tr_b16 v[218:219], v206 offset:0x2c00
	v_exp_f32_e32 v189, v103
	s_waitcnt lgkmcnt(7)
	v_mfma_f32_32x32x16_bf16 v[16:31], v[76:79], v[220:223], v[16:31]
	ds_read_b64_tr_b16 v[220:221], v206 offset:0x3400
	ds_read_b64_tr_b16 v[222:223], v206 offset:0x3c00
	v_exp_f32_e32 v196, v104
	ds_write_b128 v213, v[154:157] offset:32768
	s_waitcnt lgkmcnt(7)
	v_mfma_f32_32x32x16_bf16 v[32:47], v[64:67], v[180:183], v[32:47]
	ds_read_b64_tr_b16 v[180:181], v206 offset:0x600
	ds_read_b64_tr_b16 v[182:183], v206 offset:0xe00
	v_exp_f32_e32 v197, v105
	s_waitcnt lgkmcnt(7)
	v_mfma_f32_32x32x16_bf16 v[32:47], v[68:71], v[184:187], v[32:47]
	ds_read_b64_tr_b16 v[184:185], v206 offset:0x1600
	ds_read_b64_tr_b16 v[186:187], v206 offset:0x1e00
	v_exp_f32_e32 v198, v106
	s_waitcnt lgkmcnt(7)
	v_mfma_f32_32x32x16_bf16 v[32:47], v[72:75], v[216:219], v[32:47]
	ds_read_b64_tr_b16 v[216:217], v206 offset:0x2600
	ds_read_b64_tr_b16 v[218:219], v206 offset:0x2e00
	v_exp_f32_e32 v199, v107
	s_waitcnt lgkmcnt(7)
	v_mfma_f32_32x32x16_bf16 v[32:47], v[76:79], v[220:223], v[32:47]
	ds_read_b64_tr_b16 v[220:221], v206 offset:0x3600
	ds_read_b64_tr_b16 v[222:223], v206 offset:0x3e00
	ds_write_b128 v214, v[158:161] offset:32768
	s_waitcnt lgkmcnt(7)
	v_mfma_f32_32x32x16_bf16 v[48:63], v[64:67], v[180:183], v[48:63]
	s_waitcnt vmcnt(4)
	v_exp_f32_e32 v181, v96
	v_exp_f32_e32 v183, v97
	s_waitcnt lgkmcnt(5)
	v_mfma_f32_32x32x16_bf16 v[48:63], v[68:71], v[184:187], v[48:63]
	v_exp_f32_e32 v184, v98
	v_exp_f32_e32 v185, v99
	v_exp_f32_e32 v186, v100
	v_exp_f32_e32 v187, v101
	s_waitcnt lgkmcnt(3)
	v_mfma_f32_32x32x16_bf16 v[48:63], v[72:75], v[216:219], v[48:63]
	v_exp_f32_e32 v216, v109
	v_exp_f32_e32 v217, v110
	v_exp_f32_e32 v218, v111
	s_waitcnt lgkmcnt(0)
	s_barrier
	v_mfma_f32_32x32x16_bf16 v[48:63], v[76:79], v[220:223], v[48:63]
	ds_read_b128 v[64:67], v207 offset:32768
	ds_read_b128 v[96:99], v207 offset:40960
	ds_read_b128 v[146:149], v208 offset:32768
	ds_read_b128 v[150:153], v208 offset:40960
	v_exp_f32_e32 v154, v88
	v_exp_f32_e32 v155, v89
	v_exp_f32_e32 v156, v90
	v_exp_f32_e32 v157, v91
	v_exp_f32_e32 v158, v92
	v_exp_f32_e32 v159, v93
	v_exp_f32_e32 v160, v94
	v_exp_f32_e32 v95, v95
	s_waitcnt lgkmcnt(3)
	v_mfma_f32_32x32x16_bf16 v[64:79], v[64:67], v[142:145], 0
	v_exp_f32_e32 v236, v80
	v_add_f32_e32 v80, 0, v181
	v_add_f32_e32 v80, v183, v80
	v_add_f32_e32 v80, v184, v80
	s_waitcnt lgkmcnt(2)
	v_mfma_f32_32x32x16_bf16 v[96:111], v[96:99], v[142:145], 0
	v_add_f32_e32 v80, v185, v80
	v_add_f32_e32 v80, v186, v80
	v_add_f32_e32 v80, v187, v80
	s_waitcnt lgkmcnt(1)
	v_mfma_f32_32x32x16_bf16 v[64:79], v[146:149], v[138:141], v[64:79]
	v_add_f32_e32 v80, v188, v80
	v_add_f32_e32 v80, v189, v80
	v_add_f32_e32 v80, v196, v80
	s_waitcnt lgkmcnt(0)
	v_mfma_f32_32x32x16_bf16 v[96:111], v[150:153], v[138:141], v[96:111]
	ds_read_b128 v[146:149], v209 offset:32768
	ds_read_b128 v[150:153], v209 offset:40960
	v_add_f32_e32 v80, v197, v80
	v_add_f32_e32 v80, v198, v80
	v_add_f32_e32 v80, v199, v80
	v_add_f32_e32 v80, v215, v80
	v_exp_f32_e32 v237, v81
	s_waitcnt lgkmcnt(1)
	v_mfma_f32_32x32x16_bf16 v[64:79], v[146:149], v[112:115], v[64:79]
	v_add_f32_e32 v80, v216, v80
	v_exp_f32_e32 v238, v82
	v_add_f32_e32 v80, v217, v80
	v_exp_f32_e32 v239, v83
	s_waitcnt lgkmcnt(0)
	v_mfma_f32_32x32x16_bf16 v[96:111], v[150:153], v[112:115], v[96:111]
	ds_read_b128 v[146:149], v210 offset:32768
	ds_read_b128 v[150:153], v210 offset:40960
	v_add_f32_e32 v80, v218, v80
	v_exp_f32_e32 v247, v84
	v_add_f32_e32 v80, v236, v80
	v_exp_f32_e32 v248, v85
	s_waitcnt lgkmcnt(1)
	v_mfma_f32_32x32x16_bf16 v[64:79], v[146:149], v[116:119], v[64:79]
	v_add_f32_e32 v80, v237, v80
	v_exp_f32_e32 v249, v86
	v_add_f32_e32 v80, v238, v80
	v_exp_f32_e32 v252, v87
	s_waitcnt lgkmcnt(0)
	v_mfma_f32_32x32x16_bf16 v[96:111], v[150:153], v[116:119], v[96:111]
	ds_read_b128 v[146:149], v190 offset:32768
	ds_read_b128 v[150:153], v190 offset:40960
	v_add_f32_e32 v80, v239, v80
	v_add_f32_e32 v80, v247, v80
	v_add_f32_e32 v80, v248, v80
	v_add_f32_e32 v80, v249, v80
	v_add_f32_e32 v80, v252, v80
	v_add_f32_e32 v80, v154, v80
	s_waitcnt lgkmcnt(1)
	v_mfma_f32_32x32x16_bf16 v[64:79], v[146:149], v[120:123], v[64:79]
	v_add_f32_e32 v80, v155, v80
	v_add_f32_e32 v80, v156, v80
	v_add_f32_e32 v80, v157, v80
	v_add_f32_e32 v80, v158, v80
	v_add_f32_e32 v80, v159, v80
	s_waitcnt lgkmcnt(0)
	v_mfma_f32_32x32x16_bf16 v[96:111], v[150:153], v[120:123], v[96:111]
	ds_read_b128 v[146:149], v191 offset:32768
	ds_read_b128 v[150:153], v191 offset:40960
	v_add_f32_e32 v80, v160, v80
	v_add_f32_e32 v180, v95, v80
	v_mov_b32_e32 v182, v180
	v_cvt_pk_bf16_f32 v80, v181, v183
	v_cvt_pk_bf16_f32 v81, v184, v185
	v_cvt_pk_bf16_f32 v82, v186, v187
	s_waitcnt lgkmcnt(1)
; #define SBAR() __builtin_amdgcn_sched_barrier(0)
; __device__ __forceinline__ void finishSM(f32x16& p0, f32x16& p1, float alpha, float& l_reg, bf16x8& pa0, bf16x8& pa1, bf16x8& pa2, bf16x8& pa3) {
;   for (int r = 0; r < 16; ++r) p1[r] = __builtin_amdgcn_exp2f(p1[r]);
;   float ps = 0; for (int r = 0; r < 16; ++r) ps += p0[r]; for (int r = 0; r < 16; ++r) ps += p1[r];
;   { auto rr = __builtin_amdgcn_permlane32_swap(__float_as_uint(ps), __float_as_uint(ps), false, false);
;     ps = __uint_as_float(rr[0]) + __uint_as_float(rr[1]); }
;   l_reg = l_reg * alpha + ps;
;     ...
;   PK4(p0, 0, pa0); PK4(p0, 8, pa1); PK4(p1, 0, pa2); PK4(p1, 8, pa3);
;     ...
; }
; template <int D0, int BOFF> __device__ __forceinline__ void pv_one_i(f32x16& od, int vb, bf16x8 pa0, bf16x8 pa1, bf16x8 pa2, bf16x8 pa3) {
;   const s16x4 l0 = tr_read<BOFF + v_rd_off(D0, 0, 0)>(vb), h0 = tr_read<BOFF + v_rd_off(D0, 0, 1)>(vb), l1 = tr_read<BOFF + v_rd_off(D0, 1, 0)>(vb), h1 = tr_read<BOFF + v_rd_off(D0, 1, 1)>(vb);
;   const s16x4 l2 = tr_read<BOFF + v_rd_off(D0, 2, 0)>(vb), h2 = tr_read<BOFF + v_rd_off(D0, 2, 1)>(vb), l3 = tr_read<BOFF + v_rd_off(D0, 3, 0)>(vb), h3 = tr_read<BOFF + v_rd_off(D0, 3, 1)>(vb);
;   asm volatile("s_waitcnt lgkmcnt(0)" ::: "memory"); SBAR();
;     ...
;   od = __builtin_amdgcn_mfma_f32_32x32x16_bf16(pa0, PK(l0, h0), od, 0, 0, 0);
;   od = __builtin_amdgcn_mfma_f32_32x32x16_bf16(pa1, PK(l1, h1), od, 0, 0, 0);
;   od = __builtin_amdgcn_mfma_f32_32x32x16_bf16(pa2, PK(l2, h2), od, 0, 0, 0);
;   od = __builtin_amdgcn_mfma_f32_32x32x16_bf16(pa3, PK(l3, h3), od, 0, 0, 0);
;     ...
; }
; template <int BOFF> __device__ __forceinline__ void pv_i(f32x16* o, int vb, bf16x8 pa0, bf16x8 pa1, bf16x8 pa2, bf16x8 pa3) {
;   pv_one_i<0, BOFF>(o[0], vb, pa0, pa1, pa2, pa3); pv_one_i<1, BOFF>(o[1], vb, pa0, pa1, pa2, pa3); pv_one_i<2, BOFF>(o[2], vb, pa0, pa1, pa2, pa3); pv_one_i<3, BOFF>(o[3], vb, pa0, pa1, pa2, pa3);
; }
	v_mfma_f32_32x32x16_bf16 v[64:79], v[146:149], v[124:127], v[64:79]
	v_cvt_pk_bf16_f32 v83, v188, v189
	v_cvt_pk_bf16_f32 v84, v196, v197
	v_cvt_pk_bf16_f32 v85, v198, v199
	v_cvt_pk_bf16_f32 v86, v215, v216
	v_cvt_pk_bf16_f32 v87, v217, v218
	s_waitcnt lgkmcnt(0)
	v_mfma_f32_32x32x16_bf16 v[96:111], v[150:153], v[124:127], v[96:111]
	ds_read_b128 v[146:149], v192 offset:32768
	ds_read_b128 v[150:153], v192 offset:40960
	v_cvt_pk_bf16_f32 v88, v236, v237
	v_cvt_pk_bf16_f32 v89, v238, v239
	v_cvt_pk_bf16_f32 v90, v247, v248
	v_cvt_pk_bf16_f32 v91, v249, v252
	v_cvt_pk_bf16_f32 v92, v154, v155
	v_cvt_pk_bf16_f32 v93, v156, v157
	s_waitcnt lgkmcnt(1)
	v_mfma_f32_32x32x16_bf16 v[64:79], v[146:149], v[130:133], v[64:79]
	v_cvt_pk_bf16_f32 v94, v158, v159
	v_cvt_pk_bf16_f32 v95, v160, v95
	s_nop 1
	v_permlane32_swap_b32_e32 v180, v182
	v_permlane32_swap_b32_e32 v80, v82
	s_waitcnt lgkmcnt(0)
	v_mfma_f32_32x32x16_bf16 v[96:111], v[150:153], v[130:133], v[96:111]
	ds_read_b128 v[146:149], v193 offset:32768
	ds_read_b128 v[150:153], v193 offset:40960
	ds_read_b64_tr_b16 v[184:185], v206 offset:0x4000
	ds_read_b64_tr_b16 v[186:187], v206 offset:0x4800
	ds_read_b64_tr_b16 v[216:217], v206 offset:0x5000
	ds_read_b64_tr_b16 v[218:219], v206 offset:0x5800
	ds_read_b64_tr_b16 v[220:221], v206 offset:0x6000
	ds_read_b64_tr_b16 v[222:223], v206 offset:0x6800
	ds_read_b64_tr_b16 v[224:225], v206 offset:0x7000
	ds_read_b64_tr_b16 v[226:227], v206 offset:0x7800
	v_permlane32_swap_b32_e32 v81, v83
	v_permlane32_swap_b32_e32 v84, v86
	v_permlane32_swap_b32_e32 v85, v87
	v_permlane32_swap_b32_e32 v88, v90
	v_permlane32_swap_b32_e32 v89, v91
	v_permlane32_swap_b32_e32 v92, v94
	s_waitcnt lgkmcnt(9)
	v_mfma_f32_32x32x16_bf16 v[64:79], v[146:149], v[134:137], v[64:79]
	v_permlane32_swap_b32_e32 v93, v95
	s_waitcnt lgkmcnt(8)
	v_mfma_f32_32x32x16_bf16 v[96:111], v[150:153], v[134:137], v[96:111]
	s_waitcnt vmcnt(0)
	ds_write_b128 v211, v[162:165]
	s_nop 0
	s_waitcnt lgkmcnt(7)
	v_mfma_f32_32x32x16_bf16 v[0:15], v[80:83], v[184:187], v[0:15]
	ds_read_b64_tr_b16 v[184:185], v206 offset:0x4200
	ds_read_b64_tr_b16 v[186:187], v206 offset:0x4a00
	v_add_co_u32_e32 v150, vcc, s21, v178
	s_nop 1
	v_addc_co_u32_e32 v151, vcc, -1, v179, vcc
	v_add_co_u32_e32 v154, vcc, s22, v178
	s_nop 1
	v_addc_co_u32_e32 v155, vcc, -1, v179, vcc
	s_waitcnt lgkmcnt(7)
	v_mfma_f32_32x32x16_bf16 v[0:15], v[84:87], v[216:219], v[0:15]
	ds_read_b64_tr_b16 v[216:217], v206 offset:0x5200
	ds_read_b64_tr_b16 v[218:219], v206 offset:0x5a00
	global_load_dwordx4 v[146:149], v[150:151], off
	s_nop 0
	global_load_dwordx4 v[150:153], v[150:151], off offset:-512
	s_nop 0
	global_load_dwordx4 v[158:161], v[154:155], off
	s_nop 0
	global_load_dwordx4 v[154:157], v[154:155], off offset:-512
	s_waitcnt lgkmcnt(7)
	v_mfma_f32_32x32x16_bf16 v[0:15], v[88:91], v[220:223], v[0:15]
	ds_read_b64_tr_b16 v[220:221], v206 offset:0x6200
	ds_read_b64_tr_b16 v[222:223], v206 offset:0x6a00
	s_waitcnt lgkmcnt(7)
	v_mfma_f32_32x32x16_bf16 v[0:15], v[92:95], v[224:227], v[0:15]
	ds_read_b64_tr_b16 v[224:225], v206 offset:0x7200
	ds_read_b64_tr_b16 v[226:227], v206 offset:0x7a00
	ds_write_b128 v212, v[174:177]
	s_waitcnt lgkmcnt(7)
	v_mfma_f32_32x32x16_bf16 v[16:31], v[80:83], v[184:187], v[16:31]
	ds_read_b64_tr_b16 v[184:185], v206 offset:0x4400
	ds_read_b64_tr_b16 v[186:187], v206 offset:0x4c00
	v_exp_f32_e32 v215, v74
	s_waitcnt lgkmcnt(7)
	v_mfma_f32_32x32x16_bf16 v[16:31], v[84:87], v[216:219], v[16:31]
	ds_read_b64_tr_b16 v[216:217], v206 offset:0x5400
	ds_read_b64_tr_b16 v[218:219], v206 offset:0x5c00
	v_exp_f32_e32 v188, v68
	s_waitcnt lgkmcnt(7)
	v_mfma_f32_32x32x16_bf16 v[16:31], v[88:91], v[220:223], v[16:31]
	ds_read_b64_tr_b16 v[220:221], v206 offset:0x6400
	ds_read_b64_tr_b16 v[222:223], v206 offset:0x6c00
	v_exp_f32_e32 v189, v69
	s_waitcnt lgkmcnt(7)
	v_mfma_f32_32x32x16_bf16 v[16:31], v[92:95], v[224:227], v[16:31]
	ds_read_b64_tr_b16 v[224:225], v206 offset:0x7400
	ds_read_b64_tr_b16 v[226:227], v206 offset:0x7c00
	v_exp_f32_e32 v196, v70
	ds_write_b128 v213, v[166:169]
	s_waitcnt lgkmcnt(7)
	v_mfma_f32_32x32x16_bf16 v[32:47], v[80:83], v[184:187], v[32:47]
	ds_read_b64_tr_b16 v[184:185], v206 offset:0x4600
	ds_read_b64_tr_b16 v[186:187], v206 offset:0x4e00
	v_exp_f32_e32 v197, v71
	s_waitcnt lgkmcnt(7)
	v_mfma_f32_32x32x16_bf16 v[32:47], v[84:87], v[216:219], v[32:47]
	ds_read_b64_tr_b16 v[216:217], v206 offset:0x5600
	ds_read_b64_tr_b16 v[218:219], v206 offset:0x5e00
	v_exp_f32_e32 v198, v72
	s_waitcnt lgkmcnt(7)
	v_mfma_f32_32x32x16_bf16 v[32:47], v[88:91], v[220:223], v[32:47]
	ds_read_b64_tr_b16 v[220:221], v206 offset:0x6600
	ds_read_b64_tr_b16 v[222:223], v206 offset:0x6e00
	v_exp_f32_e32 v199, v73
	s_waitcnt lgkmcnt(7)
	v_mfma_f32_32x32x16_bf16 v[32:47], v[92:95], v[224:227], v[32:47]
	ds_read_b64_tr_b16 v[224:225], v206 offset:0x7600
	ds_read_b64_tr_b16 v[226:227], v206 offset:0x7e00
	ds_write_b128 v214, v[170:173]
	s_waitcnt lgkmcnt(7)
	v_mfma_f32_32x32x16_bf16 v[48:63], v[80:83], v[184:187], v[48:63]
	s_waitcnt vmcnt(4)
	v_exp_f32_e32 v184, v64
	v_exp_f32_e32 v185, v65
	v_exp_f32_e32 v186, v66
	v_exp_f32_e32 v187, v67
	s_waitcnt lgkmcnt(5)
	v_mfma_f32_32x32x16_bf16 v[48:63], v[84:87], v[216:219], v[48:63]
	v_exp_f32_e32 v219, v78
	v_exp_f32_e32 v216, v75
	s_waitcnt lgkmcnt(3)
	v_mfma_f32_32x32x16_bf16 v[48:63], v[88:91], v[220:223], v[48:63]
	v_exp_f32_e32 v220, v79
	v_exp_f32_e32 v217, v76
	v_exp_f32_e32 v218, v77
	s_waitcnt lgkmcnt(0)
	s_barrier
; __device__ __forceinline__ void finishSM(f32x16& p0, f32x16& p1, float alpha, float& l_reg, bf16x8& pa0, bf16x8& pa1, bf16x8& pa2, bf16x8& pa3) {
;   for (int r = 0; r < 16; ++r) p1[r] = __builtin_amdgcn_exp2f(p1[r]);
;   float ps = 0; for (int r = 0; r < 16; ++r) ps += p0[r]; for (int r = 0; r < 16; ++r) ps += p1[r];
;   { auto rr = __builtin_amdgcn_permlane32_swap(__float_as_uint(ps), __float_as_uint(ps), false, false);
;     ps = __uint_as_float(rr[0]) + __uint_as_float(rr[1]); }
;   l_reg = l_reg * alpha + ps;
;     ...
;   PK4(p0, 0, pa0); PK4(p0, 8, pa1); PK4(p1, 0, pa2); PK4(p1, 8, pa3);
;     ...
; }
	v_mfma_f32_32x32x16_bf16 v[48:63], v[92:95], v[224:227], v[48:63]
	ds_read_b128 v[64:67], v207
	ds_read_b128 v[68:71], v207 offset:8192
	ds_read_b128 v[162:165], v208
	ds_read_b128 v[166:169], v208 offset:8192
	v_exp_f32_e32 v170, v104
	v_exp_f32_e32 v171, v105
	v_exp_f32_e32 v172, v106
	v_exp_f32_e32 v173, v107
	v_exp_f32_e32 v174, v108
	v_exp_f32_e32 v175, v109
	v_exp_f32_e32 v176, v110
	v_exp_f32_e32 v111, v111
	s_waitcnt lgkmcnt(3)
	v_mfma_f32_32x32x16_bf16 v[80:95], v[64:67], v[142:145], 0
	v_exp_f32_e32 v236, v96
	v_add_f32_e32 v96, 0, v184
	v_add_f32_e32 v96, v185, v96
	v_add_f32_e32 v96, v186, v96
	s_waitcnt lgkmcnt(2)
	v_mfma_f32_32x32x16_bf16 v[64:79], v[68:71], v[142:145], 0
	v_add_f32_e32 v96, v187, v96
	v_add_f32_e32 v96, v188, v96
	v_add_f32_e32 v96, v189, v96
	s_waitcnt lgkmcnt(1)
	v_mfma_f32_32x32x16_bf16 v[80:95], v[162:165], v[138:141], v[80:95]
	v_add_f32_e32 v96, v196, v96
	v_add_f32_e32 v96, v197, v96
	v_add_f32_e32 v96, v198, v96
	s_waitcnt lgkmcnt(0)
	v_mfma_f32_32x32x16_bf16 v[64:79], v[166:169], v[138:141], v[64:79]
	ds_read_b128 v[162:165], v209
	ds_read_b128 v[166:169], v209 offset:8192
	v_add_f32_e32 v96, v199, v96
	v_add_f32_e32 v96, v215, v96
	v_add_f32_e32 v96, v216, v96
	v_add_f32_e32 v96, v217, v96
	v_exp_f32_e32 v237, v97
	s_waitcnt lgkmcnt(1)
	v_mfma_f32_32x32x16_bf16 v[80:95], v[162:165], v[112:115], v[80:95]
	v_add_f32_e32 v96, v218, v96
	v_exp_f32_e32 v238, v98
	v_add_f32_e32 v96, v219, v96
	v_exp_f32_e32 v239, v99
	s_waitcnt lgkmcnt(0)
	v_mfma_f32_32x32x16_bf16 v[64:79], v[166:169], v[112:115], v[64:79]
	ds_read_b128 v[162:165], v210
	ds_read_b128 v[166:169], v210 offset:8192
	v_add_f32_e32 v96, v220, v96
	v_exp_f32_e32 v247, v100
	v_add_f32_e32 v96, v236, v96
	v_exp_f32_e32 v248, v101
	s_waitcnt lgkmcnt(1)
	v_mfma_f32_32x32x16_bf16 v[80:95], v[162:165], v[116:119], v[80:95]
	v_add_f32_e32 v96, v237, v96
	v_exp_f32_e32 v249, v102
	v_add_f32_e32 v96, v238, v96
	v_exp_f32_e32 v252, v103
	s_waitcnt lgkmcnt(0)
	v_mfma_f32_32x32x16_bf16 v[64:79], v[166:169], v[116:119], v[64:79]
	ds_read_b128 v[162:165], v190 offset:0
	ds_read_b128 v[166:169], v190 offset:8192
	v_add_f32_e32 v96, v239, v96
	v_add_f32_e32 v96, v247, v96
	v_add_f32_e32 v96, v248, v96
	v_add_f32_e32 v96, v249, v96
	v_add_f32_e32 v96, v252, v96
	v_add_f32_e32 v96, v170, v96
	s_waitcnt lgkmcnt(1)
	v_mfma_f32_32x32x16_bf16 v[80:95], v[162:165], v[120:123], v[80:95]
	v_add_f32_e32 v96, v171, v96
	v_add_f32_e32 v96, v172, v96
	v_add_f32_e32 v96, v173, v96
	v_add_f32_e32 v96, v174, v96
	v_add_f32_e32 v96, v175, v96
	s_waitcnt lgkmcnt(0)
	v_mfma_f32_32x32x16_bf16 v[64:79], v[166:169], v[120:123], v[64:79]
	ds_read_b128 v[162:165], v191 offset:0
	ds_read_b128 v[166:169], v191 offset:8192
	v_add_f32_e32 v96, v176, v96
	v_add_f32_e32 v181, v111, v96
	v_mov_b32_e32 v183, v181
	s_nop 1
	v_permlane32_swap_b32_e32 v181, v183
	v_pk_add_f32 v[96:97], v[180:181], v[182:183]
	s_waitcnt lgkmcnt(1)
	v_mfma_f32_32x32x16_bf16 v[80:95], v[162:165], v[124:127], v[80:95]
	s_nop 0
	v_add_f32_e32 v96, v128, v96
	v_add_f32_e32 v128, v96, v97
	v_cvt_pk_bf16_f32 v96, v184, v185
	v_cvt_pk_bf16_f32 v97, v186, v187
	s_waitcnt lgkmcnt(0)
	v_mfma_f32_32x32x16_bf16 v[64:79], v[166:169], v[124:127], v[64:79]
	ds_read_b128 v[162:165], v192 offset:0
	ds_read_b128 v[166:169], v192 offset:8192
	v_cvt_pk_bf16_f32 v98, v188, v189
	v_cvt_pk_bf16_f32 v99, v196, v197
	v_cvt_pk_bf16_f32 v100, v198, v199
	v_cvt_pk_bf16_f32 v101, v215, v216
	v_cvt_pk_bf16_f32 v102, v217, v218
	v_cvt_pk_bf16_f32 v103, v219, v220
	s_waitcnt lgkmcnt(1)
	v_mfma_f32_32x32x16_bf16 v[80:95], v[162:165], v[130:133], v[80:95]
	v_cvt_pk_bf16_f32 v104, v236, v237
	v_cvt_pk_bf16_f32 v105, v238, v239
	v_cvt_pk_bf16_f32 v106, v247, v248
	v_cvt_pk_bf16_f32 v107, v249, v252
	v_cvt_pk_bf16_f32 v108, v170, v171
	s_waitcnt lgkmcnt(0)
	v_mfma_f32_32x32x16_bf16 v[64:79], v[166:169], v[130:133], v[64:79]
	ds_read_b128 v[162:165], v193 offset:0
	ds_read_b128 v[166:169], v193 offset:8192
	ds_read_b64_tr_b16 v[180:181], v206 offset:0x8000
	ds_read_b64_tr_b16 v[182:183], v206 offset:0x8800
	ds_read_b64_tr_b16 v[184:185], v206 offset:0x9000
	ds_read_b64_tr_b16 v[186:187], v206 offset:0x9800
	ds_read_b64_tr_b16 v[216:217], v206 offset:0xa000
	ds_read_b64_tr_b16 v[218:219], v206 offset:0xa800
	ds_read_b64_tr_b16 v[220:221], v206 offset:0xb000
	ds_read_b64_tr_b16 v[222:223], v206 offset:0xb800
	v_cvt_pk_bf16_f32 v109, v172, v173
	v_cvt_pk_bf16_f32 v110, v174, v175
	v_cvt_pk_bf16_f32 v111, v176, v111
	s_nop 0
	v_permlane32_swap_b32_e32 v96, v98
	v_permlane32_swap_b32_e32 v97, v99
	s_waitcnt lgkmcnt(9)
	v_mfma_f32_32x32x16_bf16 v[80:95], v[162:165], v[134:137], v[80:95]
	v_permlane32_swap_b32_e32 v100, v102
	v_permlane32_swap_b32_e32 v101, v103
	v_permlane32_swap_b32_e32 v104, v106
	v_permlane32_swap_b32_e32 v105, v107
	v_permlane32_swap_b32_e32 v108, v110
	s_waitcnt lgkmcnt(8)
	v_mfma_f32_32x32x16_bf16 v[64:79], v[166:169], v[134:137], v[64:79]
	v_permlane32_swap_b32_e32 v109, v111
	s_waitcnt vmcnt(0)
	ds_write_b128 v211, v[146:149] offset:16384
	s_nop 0
	s_waitcnt lgkmcnt(7)
	v_mfma_f32_32x32x16_bf16 v[0:15], v[96:99], v[180:183], v[0:15]
	ds_read_b64_tr_b16 v[180:181], v206 offset:0x8200
	ds_read_b64_tr_b16 v[182:183], v206 offset:0x8a00
	v_add_co_u32_e32 v166, vcc, s23, v178
	s_nop 1
	v_addc_co_u32_e32 v167, vcc, -1, v179, vcc
	v_add_co_u32_e32 v170, vcc, s24, v178
	s_nop 1
	v_addc_co_u32_e32 v171, vcc, -1, v179, vcc
	s_waitcnt lgkmcnt(7)
; #define SBAR() __builtin_amdgcn_sched_barrier(0)
; template <int D0, int BOFF> __device__ __forceinline__ void pv_one_i(f32x16& od, int vb, bf16x8 pa0, bf16x8 pa1, bf16x8 pa2, bf16x8 pa3) {
;   const s16x4 l0 = tr_read<BOFF + v_rd_off(D0, 0, 0)>(vb), h0 = tr_read<BOFF + v_rd_off(D0, 0, 1)>(vb), l1 = tr_read<BOFF + v_rd_off(D0, 1, 0)>(vb), h1 = tr_read<BOFF + v_rd_off(D0, 1, 1)>(vb);
;   const s16x4 l2 = tr_read<BOFF + v_rd_off(D0, 2, 0)>(vb), h2 = tr_read<BOFF + v_rd_off(D0, 2, 1)>(vb), l3 = tr_read<BOFF + v_rd_off(D0, 3, 0)>(vb), h3 = tr_read<BOFF + v_rd_off(D0, 3, 1)>(vb);
;   asm volatile("s_waitcnt lgkmcnt(0)" ::: "memory"); SBAR();
;     ...
;   od = __builtin_amdgcn_mfma_f32_32x32x16_bf16(pa0, PK(l0, h0), od, 0, 0, 0);
;   od = __builtin_amdgcn_mfma_f32_32x32x16_bf16(pa1, PK(l1, h1), od, 0, 0, 0);
;   od = __builtin_amdgcn_mfma_f32_32x32x16_bf16(pa2, PK(l2, h2), od, 0, 0, 0);
;   od = __builtin_amdgcn_mfma_f32_32x32x16_bf16(pa3, PK(l3, h3), od, 0, 0, 0);
;     ...
; }
; template <int BOFF> __device__ __forceinline__ void pv_i(f32x16* o, int vb, bf16x8 pa0, bf16x8 pa1, bf16x8 pa2, bf16x8 pa3) {
;   pv_one_i<0, BOFF>(o[0], vb, pa0, pa1, pa2, pa3); pv_one_i<1, BOFF>(o[1], vb, pa0, pa1, pa2, pa3); pv_one_i<2, BOFF>(o[2], vb, pa0, pa1, pa2, pa3); pv_one_i<3, BOFF>(o[3], vb, pa0, pa1, pa2, pa3);
; }
	v_mfma_f32_32x32x16_bf16 v[0:15], v[100:103], v[184:187], v[0:15]
	ds_read_b64_tr_b16 v[184:185], v206 offset:0x9200
	ds_read_b64_tr_b16 v[186:187], v206 offset:0x9a00
	global_load_dwordx4 v[162:165], v[166:167], off
	s_nop 0
	global_load_dwordx4 v[166:169], v[166:167], off offset:-512
	s_nop 0
	global_load_dwordx4 v[174:177], v[170:171], off
	s_nop 0
	global_load_dwordx4 v[170:173], v[170:171], off offset:-512
	s_waitcnt lgkmcnt(7)
	v_mfma_f32_32x32x16_bf16 v[0:15], v[104:107], v[216:219], v[0:15]
	ds_read_b64_tr_b16 v[216:217], v206 offset:0xa200
	ds_read_b64_tr_b16 v[218:219], v206 offset:0xaa00
	s_waitcnt lgkmcnt(7)
	v_mfma_f32_32x32x16_bf16 v[0:15], v[108:111], v[220:223], v[0:15]
	ds_read_b64_tr_b16 v[220:221], v206 offset:0xb200
	ds_read_b64_tr_b16 v[222:223], v206 offset:0xba00
	ds_write_b128 v212, v[158:161] offset:16384
	s_waitcnt lgkmcnt(7)
	v_mfma_f32_32x32x16_bf16 v[16:31], v[96:99], v[180:183], v[16:31]
	ds_read_b64_tr_b16 v[180:181], v206 offset:0x8400
	ds_read_b64_tr_b16 v[182:183], v206 offset:0x8c00
	v_exp_f32_e32 v215, v92
	s_waitcnt lgkmcnt(7)
	v_mfma_f32_32x32x16_bf16 v[16:31], v[100:103], v[184:187], v[16:31]
	ds_read_b64_tr_b16 v[184:185], v206 offset:0x9400
	ds_read_b64_tr_b16 v[186:187], v206 offset:0x9c00
	v_exp_f32_e32 v188, v86
	s_waitcnt lgkmcnt(7)
	v_mfma_f32_32x32x16_bf16 v[16:31], v[104:107], v[216:219], v[16:31]
	ds_read_b64_tr_b16 v[216:217], v206 offset:0xa400
	ds_read_b64_tr_b16 v[218:219], v206 offset:0xac00
	v_exp_f32_e32 v189, v87
	s_waitcnt lgkmcnt(7)
	v_mfma_f32_32x32x16_bf16 v[16:31], v[108:111], v[220:223], v[16:31]
	ds_read_b64_tr_b16 v[220:221], v206 offset:0xb400
	ds_read_b64_tr_b16 v[222:223], v206 offset:0xbc00
	v_exp_f32_e32 v196, v88
	ds_write_b128 v213, v[150:153] offset:16384
	s_waitcnt lgkmcnt(7)
	v_mfma_f32_32x32x16_bf16 v[32:47], v[96:99], v[180:183], v[32:47]
	ds_read_b64_tr_b16 v[180:181], v206 offset:0x8600
	ds_read_b64_tr_b16 v[182:183], v206 offset:0x8e00
	v_exp_f32_e32 v197, v89
	s_waitcnt lgkmcnt(7)
	v_mfma_f32_32x32x16_bf16 v[32:47], v[100:103], v[184:187], v[32:47]
	ds_read_b64_tr_b16 v[184:185], v206 offset:0x9600
	ds_read_b64_tr_b16 v[186:187], v206 offset:0x9e00
	v_exp_f32_e32 v198, v90
	s_waitcnt lgkmcnt(7)
	v_mfma_f32_32x32x16_bf16 v[32:47], v[104:107], v[216:219], v[32:47]
	ds_read_b64_tr_b16 v[216:217], v206 offset:0xa600
	ds_read_b64_tr_b16 v[218:219], v206 offset:0xae00
	v_exp_f32_e32 v199, v91
	s_waitcnt lgkmcnt(7)
	v_mfma_f32_32x32x16_bf16 v[32:47], v[108:111], v[220:223], v[32:47]
	ds_read_b64_tr_b16 v[220:221], v206 offset:0xb600
	ds_read_b64_tr_b16 v[222:223], v206 offset:0xbe00
	ds_write_b128 v214, v[154:157] offset:16384
	s_waitcnt lgkmcnt(7)
	v_mfma_f32_32x32x16_bf16 v[48:63], v[96:99], v[180:183], v[48:63]
	s_waitcnt vmcnt(4)
	v_exp_f32_e32 v181, v80
	v_exp_f32_e32 v183, v81
	s_waitcnt lgkmcnt(5)
	v_mfma_f32_32x32x16_bf16 v[48:63], v[100:103], v[184:187], v[48:63]
	v_exp_f32_e32 v184, v82
	v_exp_f32_e32 v185, v83
	v_exp_f32_e32 v186, v84
	v_exp_f32_e32 v187, v85
	s_waitcnt lgkmcnt(3)
	v_mfma_f32_32x32x16_bf16 v[48:63], v[104:107], v[216:219], v[48:63]
	v_exp_f32_e32 v216, v93
	v_exp_f32_e32 v217, v94
	v_exp_f32_e32 v218, v95
	s_waitcnt lgkmcnt(0)
	s_barrier
	v_mfma_f32_32x32x16_bf16 v[48:63], v[108:111], v[220:223], v[48:63]
	ds_read_b128 v[80:83], v207 offset:16384
	ds_read_b128 v[96:99], v207 offset:24576
	ds_read_b128 v[146:149], v208 offset:16384
	ds_read_b128 v[150:153], v208 offset:24576
	v_exp_f32_e32 v154, v72
	v_exp_f32_e32 v155, v73
	v_exp_f32_e32 v156, v74
	v_exp_f32_e32 v157, v75
	v_exp_f32_e32 v158, v76
	v_exp_f32_e32 v159, v77
	v_exp_f32_e32 v160, v78
	v_exp_f32_e32 v79, v79
	s_waitcnt lgkmcnt(3)
	v_mfma_f32_32x32x16_bf16 v[80:95], v[80:83], v[142:145], 0
	v_exp_f32_e32 v236, v64
	v_add_f32_e32 v64, 0, v181
	v_add_f32_e32 v64, v183, v64
	v_add_f32_e32 v64, v184, v64
	s_waitcnt lgkmcnt(2)
	v_mfma_f32_32x32x16_bf16 v[96:111], v[96:99], v[142:145], 0
	v_add_f32_e32 v64, v185, v64
	v_add_f32_e32 v64, v186, v64
	v_add_f32_e32 v64, v187, v64
	s_waitcnt lgkmcnt(1)
	v_mfma_f32_32x32x16_bf16 v[80:95], v[146:149], v[138:141], v[80:95]
	v_add_f32_e32 v64, v188, v64
	v_add_f32_e32 v64, v189, v64
	v_add_f32_e32 v64, v196, v64
	s_waitcnt lgkmcnt(0)
	v_mfma_f32_32x32x16_bf16 v[96:111], v[150:153], v[138:141], v[96:111]
	ds_read_b128 v[146:149], v209 offset:16384
	ds_read_b128 v[150:153], v209 offset:24576
	v_add_f32_e32 v64, v197, v64
	v_add_f32_e32 v64, v198, v64
	v_add_f32_e32 v64, v199, v64
	v_add_f32_e32 v64, v215, v64
	v_exp_f32_e32 v237, v65
	s_waitcnt lgkmcnt(1)
	v_mfma_f32_32x32x16_bf16 v[80:95], v[146:149], v[112:115], v[80:95]
	v_add_f32_e32 v64, v216, v64
	v_exp_f32_e32 v238, v66
	v_add_f32_e32 v64, v217, v64
	v_exp_f32_e32 v239, v67
	s_waitcnt lgkmcnt(0)
	v_mfma_f32_32x32x16_bf16 v[96:111], v[150:153], v[112:115], v[96:111]
	ds_read_b128 v[146:149], v210 offset:16384
	ds_read_b128 v[150:153], v210 offset:24576
	v_add_f32_e32 v64, v218, v64
	v_exp_f32_e32 v247, v68
	v_add_f32_e32 v64, v236, v64
	v_exp_f32_e32 v248, v69
	s_waitcnt lgkmcnt(1)
	v_mfma_f32_32x32x16_bf16 v[80:95], v[146:149], v[116:119], v[80:95]
	v_add_f32_e32 v64, v237, v64
	v_exp_f32_e32 v249, v70
	v_add_f32_e32 v64, v238, v64
	v_exp_f32_e32 v252, v71
	s_waitcnt lgkmcnt(0)
	v_mfma_f32_32x32x16_bf16 v[96:111], v[150:153], v[116:119], v[96:111]
	ds_read_b128 v[146:149], v190 offset:16384
	ds_read_b128 v[150:153], v190 offset:24576
	v_add_f32_e32 v64, v239, v64
	v_add_f32_e32 v64, v247, v64
	v_add_f32_e32 v64, v248, v64
	v_add_f32_e32 v64, v249, v64
	v_add_f32_e32 v64, v252, v64
	v_add_f32_e32 v64, v154, v64
	s_waitcnt lgkmcnt(1)
; #define SBAR() __builtin_amdgcn_sched_barrier(0)
; __device__ __forceinline__ void finishSM(f32x16& p0, f32x16& p1, float alpha, float& l_reg, bf16x8& pa0, bf16x8& pa1, bf16x8& pa2, bf16x8& pa3) {
;   for (int r = 0; r < 16; ++r) p1[r] = __builtin_amdgcn_exp2f(p1[r]);
;   float ps = 0; for (int r = 0; r < 16; ++r) ps += p0[r]; for (int r = 0; r < 16; ++r) ps += p1[r];
;   { auto rr = __builtin_amdgcn_permlane32_swap(__float_as_uint(ps), __float_as_uint(ps), false, false);
;     ps = __uint_as_float(rr[0]) + __uint_as_float(rr[1]); }
;   l_reg = l_reg * alpha + ps;
;     ...
;   PK4(p0, 0, pa0); PK4(p0, 8, pa1); PK4(p1, 0, pa2); PK4(p1, 8, pa3);
;     ...
; }
; template <int D0, int BOFF> __device__ __forceinline__ void pv_one_i(f32x16& od, int vb, bf16x8 pa0, bf16x8 pa1, bf16x8 pa2, bf16x8 pa3) {
;   const s16x4 l0 = tr_read<BOFF + v_rd_off(D0, 0, 0)>(vb), h0 = tr_read<BOFF + v_rd_off(D0, 0, 1)>(vb), l1 = tr_read<BOFF + v_rd_off(D0, 1, 0)>(vb), h1 = tr_read<BOFF + v_rd_off(D0, 1, 1)>(vb);
;   const s16x4 l2 = tr_read<BOFF + v_rd_off(D0, 2, 0)>(vb), h2 = tr_read<BOFF + v_rd_off(D0, 2, 1)>(vb), l3 = tr_read<BOFF + v_rd_off(D0, 3, 0)>(vb), h3 = tr_read<BOFF + v_rd_off(D0, 3, 1)>(vb);
;   asm volatile("s_waitcnt lgkmcnt(0)" ::: "memory"); SBAR();
;     ...
;   od = __builtin_amdgcn_mfma_f32_32x32x16_bf16(pa0, PK(l0, h0), od, 0, 0, 0);
;   od = __builtin_amdgcn_mfma_f32_32x32x16_bf16(pa1, PK(l1, h1), od, 0, 0, 0);
;   od = __builtin_amdgcn_mfma_f32_32x32x16_bf16(pa2, PK(l2, h2), od, 0, 0, 0);
;   od = __builtin_amdgcn_mfma_f32_32x32x16_bf16(pa3, PK(l3, h3), od, 0, 0, 0);
;     ...
; }
; template <int BOFF> __device__ __forceinline__ void pv_i(f32x16* o, int vb, bf16x8 pa0, bf16x8 pa1, bf16x8 pa2, bf16x8 pa3) {
;   pv_one_i<0, BOFF>(o[0], vb, pa0, pa1, pa2, pa3); pv_one_i<1, BOFF>(o[1], vb, pa0, pa1, pa2, pa3); pv_one_i<2, BOFF>(o[2], vb, pa0, pa1, pa2, pa3); pv_one_i<3, BOFF>(o[3], vb, pa0, pa1, pa2, pa3);
; }
	v_mfma_f32_32x32x16_bf16 v[80:95], v[146:149], v[120:123], v[80:95]
	v_add_f32_e32 v64, v155, v64
	v_add_f32_e32 v64, v156, v64
	v_add_f32_e32 v64, v157, v64
	v_add_f32_e32 v64, v158, v64
	v_add_f32_e32 v64, v159, v64
	s_waitcnt lgkmcnt(0)
	v_mfma_f32_32x32x16_bf16 v[96:111], v[150:153], v[120:123], v[96:111]
	ds_read_b128 v[146:149], v191 offset:16384
	ds_read_b128 v[150:153], v191 offset:24576
	v_add_f32_e32 v64, v160, v64
	v_add_f32_e32 v180, v79, v64
	v_cvt_pk_bf16_f32 v64, v181, v183
	v_cvt_pk_bf16_f32 v65, v184, v185
	v_cvt_pk_bf16_f32 v66, v186, v187
	v_cvt_pk_bf16_f32 v67, v188, v189
	s_waitcnt lgkmcnt(1)
	v_mfma_f32_32x32x16_bf16 v[80:95], v[146:149], v[124:127], v[80:95]
	v_cvt_pk_bf16_f32 v68, v196, v197
	v_cvt_pk_bf16_f32 v69, v198, v199
	v_cvt_pk_bf16_f32 v70, v215, v216
	v_cvt_pk_bf16_f32 v71, v217, v218
	v_cvt_pk_bf16_f32 v72, v236, v237
	s_waitcnt lgkmcnt(0)
	v_mfma_f32_32x32x16_bf16 v[96:111], v[150:153], v[124:127], v[96:111]
	ds_read_b128 v[146:149], v192 offset:16384
	ds_read_b128 v[150:153], v192 offset:24576
	v_cvt_pk_bf16_f32 v73, v238, v239
	v_cvt_pk_bf16_f32 v74, v247, v248
	v_cvt_pk_bf16_f32 v75, v249, v252
	v_cvt_pk_bf16_f32 v76, v154, v155
	v_cvt_pk_bf16_f32 v77, v156, v157
	v_cvt_pk_bf16_f32 v78, v158, v159
	s_waitcnt lgkmcnt(1)
	v_mfma_f32_32x32x16_bf16 v[80:95], v[146:149], v[130:133], v[80:95]
	v_cvt_pk_bf16_f32 v79, v160, v79
	v_mov_b32_e32 v182, v180
	v_permlane32_swap_b32_e32 v64, v66
	v_permlane32_swap_b32_e32 v65, v67
	v_permlane32_swap_b32_e32 v68, v70
	s_waitcnt lgkmcnt(0)
	v_mfma_f32_32x32x16_bf16 v[96:111], v[150:153], v[130:133], v[96:111]
	ds_read_b128 v[146:149], v193 offset:16384
	ds_read_b128 v[150:153], v193 offset:24576
	ds_read_b64_tr_b16 v[184:185], v206 offset:0
	ds_read_b64_tr_b16 v[186:187], v206 offset:0x800
	ds_read_b64_tr_b16 v[216:217], v206 offset:0x1000
	ds_read_b64_tr_b16 v[218:219], v206 offset:0x1800
	ds_read_b64_tr_b16 v[220:221], v206 offset:0x2000
	ds_read_b64_tr_b16 v[222:223], v206 offset:0x2800
	ds_read_b64_tr_b16 v[224:225], v206 offset:0x3000
	ds_read_b64_tr_b16 v[226:227], v206 offset:0x3800
	v_permlane32_swap_b32_e32 v69, v71
	v_permlane32_swap_b32_e32 v72, v74
	v_permlane32_swap_b32_e32 v73, v75
	v_permlane32_swap_b32_e32 v76, v78
	v_permlane32_swap_b32_e32 v77, v79
	v_permlane32_swap_b32_e32 v180, v182
	s_waitcnt lgkmcnt(9)
	v_mfma_f32_32x32x16_bf16 v[80:95], v[146:149], v[134:137], v[80:95]
	s_waitcnt lgkmcnt(8)
	v_mfma_f32_32x32x16_bf16 v[96:111], v[150:153], v[134:137], v[96:111]
	s_waitcnt vmcnt(0)
	ds_write_b128 v211, v[162:165] offset:32768
	s_nop 0
	s_waitcnt lgkmcnt(7)
	v_mfma_f32_32x32x16_bf16 v[0:15], v[64:67], v[184:187], v[0:15]
	ds_read_b64_tr_b16 v[184:185], v206 offset:0x200
	ds_read_b64_tr_b16 v[186:187], v206 offset:0xa00
	v_add_co_u32_e32 v150, vcc, s25, v178
	s_nop 1
	v_addc_co_u32_e32 v151, vcc, -1, v179, vcc
	v_add_co_u32_e32 v154, vcc, s45, v178
	s_nop 1
	v_addc_co_u32_e32 v155, vcc, -1, v179, vcc
	s_waitcnt lgkmcnt(7)
	v_mfma_f32_32x32x16_bf16 v[0:15], v[68:71], v[216:219], v[0:15]
	ds_read_b64_tr_b16 v[216:217], v206 offset:0x1200
	ds_read_b64_tr_b16 v[218:219], v206 offset:0x1a00
	global_load_dwordx4 v[146:149], v[150:151], off
	s_nop 0
	global_load_dwordx4 v[150:153], v[150:151], off offset:-512
	s_nop 0
	global_load_dwordx4 v[158:161], v[154:155], off
	s_nop 0
	global_load_dwordx4 v[154:157], v[154:155], off offset:-512
	s_waitcnt lgkmcnt(7)
	v_mfma_f32_32x32x16_bf16 v[0:15], v[72:75], v[220:223], v[0:15]
	ds_read_b64_tr_b16 v[220:221], v206 offset:0x2200
	ds_read_b64_tr_b16 v[222:223], v206 offset:0x2a00
	s_waitcnt lgkmcnt(7)
	v_mfma_f32_32x32x16_bf16 v[0:15], v[76:79], v[224:227], v[0:15]
	ds_read_b64_tr_b16 v[224:225], v206 offset:0x3200
	ds_read_b64_tr_b16 v[226:227], v206 offset:0x3a00
	ds_write_b128 v212, v[174:177] offset:32768
	s_waitcnt lgkmcnt(7)
	v_mfma_f32_32x32x16_bf16 v[16:31], v[64:67], v[184:187], v[16:31]
	ds_read_b64_tr_b16 v[184:185], v206 offset:0x400
	ds_read_b64_tr_b16 v[186:187], v206 offset:0xc00
	v_exp_f32_e32 v215, v90
	s_waitcnt lgkmcnt(7)
	v_mfma_f32_32x32x16_bf16 v[16:31], v[68:71], v[216:219], v[16:31]
	ds_read_b64_tr_b16 v[216:217], v206 offset:0x1400
	ds_read_b64_tr_b16 v[218:219], v206 offset:0x1c00
	v_exp_f32_e32 v188, v84
	s_waitcnt lgkmcnt(7)
	v_mfma_f32_32x32x16_bf16 v[16:31], v[72:75], v[220:223], v[16:31]
	ds_read_b64_tr_b16 v[220:221], v206 offset:0x2400
	ds_read_b64_tr_b16 v[222:223], v206 offset:0x2c00
	v_exp_f32_e32 v189, v85
	s_waitcnt lgkmcnt(7)
	v_mfma_f32_32x32x16_bf16 v[16:31], v[76:79], v[224:227], v[16:31]
	ds_read_b64_tr_b16 v[224:225], v206 offset:0x3400
	ds_read_b64_tr_b16 v[226:227], v206 offset:0x3c00
	v_exp_f32_e32 v196, v86
	ds_write_b128 v213, v[166:169] offset:32768
	s_waitcnt lgkmcnt(7)
	v_mfma_f32_32x32x16_bf16 v[32:47], v[64:67], v[184:187], v[32:47]
	ds_read_b64_tr_b16 v[184:185], v206 offset:0x600
	ds_read_b64_tr_b16 v[186:187], v206 offset:0xe00
	v_exp_f32_e32 v197, v87
	s_waitcnt lgkmcnt(7)
	v_mfma_f32_32x32x16_bf16 v[32:47], v[68:71], v[216:219], v[32:47]
	ds_read_b64_tr_b16 v[216:217], v206 offset:0x1600
	ds_read_b64_tr_b16 v[218:219], v206 offset:0x1e00
	v_exp_f32_e32 v198, v88
	s_waitcnt lgkmcnt(7)
	v_mfma_f32_32x32x16_bf16 v[32:47], v[72:75], v[220:223], v[32:47]
	ds_read_b64_tr_b16 v[220:221], v206 offset:0x2600
	ds_read_b64_tr_b16 v[222:223], v206 offset:0x2e00
	v_exp_f32_e32 v199, v89
	s_waitcnt lgkmcnt(7)
	v_mfma_f32_32x32x16_bf16 v[32:47], v[76:79], v[224:227], v[32:47]
	ds_read_b64_tr_b16 v[224:225], v206 offset:0x3600
	ds_read_b64_tr_b16 v[226:227], v206 offset:0x3e00
	ds_write_b128 v214, v[170:173] offset:32768
	s_waitcnt lgkmcnt(7)
	v_mfma_f32_32x32x16_bf16 v[48:63], v[64:67], v[184:187], v[48:63]
	s_waitcnt vmcnt(4)
	v_exp_f32_e32 v184, v80
	v_exp_f32_e32 v185, v81
	v_exp_f32_e32 v186, v82
	v_exp_f32_e32 v187, v83
	s_waitcnt lgkmcnt(5)
	v_mfma_f32_32x32x16_bf16 v[48:63], v[68:71], v[216:219], v[48:63]
	v_exp_f32_e32 v219, v94
	v_exp_f32_e32 v216, v91
	s_waitcnt lgkmcnt(3)
	v_mfma_f32_32x32x16_bf16 v[48:63], v[72:75], v[220:223], v[48:63]
	v_exp_f32_e32 v220, v95
	v_exp_f32_e32 v217, v92
	v_exp_f32_e32 v218, v93
	s_waitcnt lgkmcnt(0)
	s_barrier
; __device__ __forceinline__ void finishSM(f32x16& p0, f32x16& p1, float alpha, float& l_reg, bf16x8& pa0, bf16x8& pa1, bf16x8& pa2, bf16x8& pa3) {
;   for (int r = 0; r < 16; ++r) p1[r] = __builtin_amdgcn_exp2f(p1[r]);
;   float ps = 0; for (int r = 0; r < 16; ++r) ps += p0[r]; for (int r = 0; r < 16; ++r) ps += p1[r];
;   { auto rr = __builtin_amdgcn_permlane32_swap(__float_as_uint(ps), __float_as_uint(ps), false, false);
;     ps = __uint_as_float(rr[0]) + __uint_as_float(rr[1]); }
;   l_reg = l_reg * alpha + ps;
;     ...
;   PK4(p0, 0, pa0); PK4(p0, 8, pa1); PK4(p1, 0, pa2); PK4(p1, 8, pa3);
;     ...
; }
	v_mfma_f32_32x32x16_bf16 v[48:63], v[76:79], v[224:227], v[48:63]
	ds_read_b128 v[64:67], v207 offset:32768
	ds_read_b128 v[80:83], v207 offset:40960
	ds_read_b128 v[162:165], v208 offset:32768
	ds_read_b128 v[166:169], v208 offset:40960
	v_exp_f32_e32 v170, v104
	v_exp_f32_e32 v171, v105
	v_exp_f32_e32 v172, v106
	v_exp_f32_e32 v173, v107
	v_exp_f32_e32 v174, v108
	v_exp_f32_e32 v175, v109
	v_exp_f32_e32 v176, v110
	v_exp_f32_e32 v111, v111
	s_waitcnt lgkmcnt(3)
	v_mfma_f32_32x32x16_bf16 v[64:79], v[64:67], v[142:145], 0
	v_exp_f32_e32 v236, v96
	v_add_f32_e32 v96, 0, v184
	v_add_f32_e32 v96, v185, v96
	v_add_f32_e32 v96, v186, v96
	s_waitcnt lgkmcnt(2)
	v_mfma_f32_32x32x16_bf16 v[80:95], v[80:83], v[142:145], 0
	v_add_f32_e32 v96, v187, v96
	v_add_f32_e32 v96, v188, v96
	v_add_f32_e32 v96, v189, v96
	s_waitcnt lgkmcnt(1)
	v_mfma_f32_32x32x16_bf16 v[64:79], v[162:165], v[138:141], v[64:79]
	v_add_f32_e32 v96, v196, v96
	v_add_f32_e32 v96, v197, v96
	v_add_f32_e32 v96, v198, v96
	s_waitcnt lgkmcnt(0)
	v_mfma_f32_32x32x16_bf16 v[80:95], v[166:169], v[138:141], v[80:95]
	ds_read_b128 v[162:165], v209 offset:32768
	ds_read_b128 v[166:169], v209 offset:40960
	v_add_f32_e32 v96, v199, v96
	v_add_f32_e32 v96, v215, v96
	v_add_f32_e32 v96, v216, v96
	v_add_f32_e32 v96, v217, v96
	v_exp_f32_e32 v237, v97
	s_waitcnt lgkmcnt(1)
	v_mfma_f32_32x32x16_bf16 v[64:79], v[162:165], v[112:115], v[64:79]
	v_add_f32_e32 v96, v218, v96
	v_exp_f32_e32 v238, v98
	v_add_f32_e32 v96, v219, v96
	v_exp_f32_e32 v239, v99
	s_waitcnt lgkmcnt(0)
	v_mfma_f32_32x32x16_bf16 v[80:95], v[166:169], v[112:115], v[80:95]
	ds_read_b128 v[162:165], v210 offset:32768
	ds_read_b128 v[166:169], v210 offset:40960
	v_add_f32_e32 v96, v220, v96
	v_exp_f32_e32 v247, v100
	v_add_f32_e32 v96, v236, v96
	v_exp_f32_e32 v248, v101
	s_waitcnt lgkmcnt(1)
	v_mfma_f32_32x32x16_bf16 v[64:79], v[162:165], v[116:119], v[64:79]
	v_add_f32_e32 v96, v237, v96
	v_exp_f32_e32 v249, v102
	v_add_f32_e32 v96, v238, v96
	v_exp_f32_e32 v252, v103
	s_waitcnt lgkmcnt(0)
	v_mfma_f32_32x32x16_bf16 v[80:95], v[166:169], v[116:119], v[80:95]
	ds_read_b128 v[162:165], v190 offset:32768
	ds_read_b128 v[166:169], v190 offset:40960
	v_add_f32_e32 v96, v239, v96
	v_add_f32_e32 v96, v247, v96
	v_add_f32_e32 v96, v248, v96
	v_add_f32_e32 v96, v249, v96
	v_add_f32_e32 v96, v252, v96
	v_add_f32_e32 v96, v170, v96
	s_waitcnt lgkmcnt(1)
	v_mfma_f32_32x32x16_bf16 v[64:79], v[162:165], v[120:123], v[64:79]
	v_add_f32_e32 v96, v171, v96
	v_add_f32_e32 v96, v172, v96
	v_add_f32_e32 v96, v173, v96
	v_add_f32_e32 v96, v174, v96
	v_add_f32_e32 v96, v175, v96
	s_waitcnt lgkmcnt(0)
	v_mfma_f32_32x32x16_bf16 v[80:95], v[166:169], v[120:123], v[80:95]
	ds_read_b128 v[162:165], v191 offset:32768
	ds_read_b128 v[166:169], v191 offset:40960
	v_add_f32_e32 v96, v176, v96
	v_add_f32_e32 v181, v111, v96
	v_mov_b32_e32 v183, v181
	s_nop 1
	v_permlane32_swap_b32_e32 v181, v183
	v_pk_add_f32 v[96:97], v[180:181], v[182:183]
	s_waitcnt lgkmcnt(1)
	v_mfma_f32_32x32x16_bf16 v[64:79], v[162:165], v[124:127], v[64:79]
	s_nop 0
	v_add_f32_e32 v96, v128, v96
	v_add_f32_e32 v128, v96, v97
	v_cvt_pk_bf16_f32 v96, v184, v185
	v_cvt_pk_bf16_f32 v97, v186, v187
	s_waitcnt lgkmcnt(0)
	v_mfma_f32_32x32x16_bf16 v[80:95], v[166:169], v[124:127], v[80:95]
	ds_read_b128 v[162:165], v192 offset:32768
	ds_read_b128 v[166:169], v192 offset:40960
	v_cvt_pk_bf16_f32 v98, v188, v189
	v_cvt_pk_bf16_f32 v99, v196, v197
	v_cvt_pk_bf16_f32 v100, v198, v199
	v_cvt_pk_bf16_f32 v101, v215, v216
	v_cvt_pk_bf16_f32 v102, v217, v218
	v_cvt_pk_bf16_f32 v103, v219, v220
	s_waitcnt lgkmcnt(1)
	v_mfma_f32_32x32x16_bf16 v[64:79], v[162:165], v[130:133], v[64:79]
	v_cvt_pk_bf16_f32 v104, v236, v237
	v_cvt_pk_bf16_f32 v105, v238, v239
	v_cvt_pk_bf16_f32 v106, v247, v248
	v_cvt_pk_bf16_f32 v107, v249, v252
	v_cvt_pk_bf16_f32 v108, v170, v171
	s_waitcnt lgkmcnt(0)
	v_mfma_f32_32x32x16_bf16 v[80:95], v[166:169], v[130:133], v[80:95]
	ds_read_b128 v[162:165], v193 offset:32768
	ds_read_b128 v[166:169], v193 offset:40960
	ds_read_b64_tr_b16 v[180:181], v206 offset:0x4000
	ds_read_b64_tr_b16 v[182:183], v206 offset:0x4800
	ds_read_b64_tr_b16 v[184:185], v206 offset:0x5000
	ds_read_b64_tr_b16 v[186:187], v206 offset:0x5800
	ds_read_b64_tr_b16 v[216:217], v206 offset:0x6000
	ds_read_b64_tr_b16 v[218:219], v206 offset:0x6800
	ds_read_b64_tr_b16 v[220:221], v206 offset:0x7000
	ds_read_b64_tr_b16 v[222:223], v206 offset:0x7800
	v_cvt_pk_bf16_f32 v109, v172, v173
	v_cvt_pk_bf16_f32 v110, v174, v175
	v_cvt_pk_bf16_f32 v111, v176, v111
	s_nop 0
	v_permlane32_swap_b32_e32 v96, v98
	v_permlane32_swap_b32_e32 v97, v99
	s_waitcnt lgkmcnt(9)
	v_mfma_f32_32x32x16_bf16 v[64:79], v[162:165], v[134:137], v[64:79]
	v_permlane32_swap_b32_e32 v100, v102
	v_permlane32_swap_b32_e32 v101, v103
	v_permlane32_swap_b32_e32 v104, v106
	v_permlane32_swap_b32_e32 v105, v107
	v_permlane32_swap_b32_e32 v108, v110
	s_waitcnt lgkmcnt(8)
	v_mfma_f32_32x32x16_bf16 v[80:95], v[166:169], v[134:137], v[80:95]
	v_permlane32_swap_b32_e32 v109, v111
	s_waitcnt vmcnt(0)
	ds_write_b128 v211, v[146:149]
	s_nop 0
	s_waitcnt lgkmcnt(7)
	v_mfma_f32_32x32x16_bf16 v[0:15], v[96:99], v[180:183], v[0:15]
	ds_read_b64_tr_b16 v[180:181], v206 offset:0x4200
	ds_read_b64_tr_b16 v[182:183], v206 offset:0x4a00
	v_add_co_u32_e32 v166, vcc, s52, v178
	s_nop 1
	v_addc_co_u32_e32 v167, vcc, -1, v179, vcc
	v_add_co_u32_e32 v170, vcc, s53, v178
	s_nop 1
	v_addc_co_u32_e32 v171, vcc, -1, v179, vcc
	s_waitcnt lgkmcnt(7)
; #define SBAR() __builtin_amdgcn_sched_barrier(0)
; __device__ __forceinline__ void partialSM_fixed(f32x16& p0) {
;   for (int r = 0; r < 16; ++r) p0[r] = __builtin_amdgcn_exp2f(p0[r]);
; }
; __device__ __forceinline__ void finishSM(f32x16& p0, f32x16& p1, float alpha, float& l_reg, bf16x8& pa0, bf16x8& pa1, bf16x8& pa2, bf16x8& pa3) {
;   for (int r = 0; r < 16; ++r) p1[r] = __builtin_amdgcn_exp2f(p1[r]);
;   float ps = 0; for (int r = 0; r < 16; ++r) ps += p0[r]; for (int r = 0; r < 16; ++r) ps += p1[r];
;   { auto rr = __builtin_amdgcn_permlane32_swap(__float_as_uint(ps), __float_as_uint(ps), false, false);
;     ps = __uint_as_float(rr[0]) + __uint_as_float(rr[1]); }
;   l_reg = l_reg * alpha + ps;
;     ...
;   PK4(p0, 0, pa0); PK4(p0, 8, pa1); PK4(p1, 0, pa2); PK4(p1, 8, pa3);
;     ...
; }
; template <int D0, int BOFF> __device__ __forceinline__ void pv_one_i(f32x16& od, int vb, bf16x8 pa0, bf16x8 pa1, bf16x8 pa2, bf16x8 pa3) {
;   const s16x4 l0 = tr_read<BOFF + v_rd_off(D0, 0, 0)>(vb), h0 = tr_read<BOFF + v_rd_off(D0, 0, 1)>(vb), l1 = tr_read<BOFF + v_rd_off(D0, 1, 0)>(vb), h1 = tr_read<BOFF + v_rd_off(D0, 1, 1)>(vb);
;   const s16x4 l2 = tr_read<BOFF + v_rd_off(D0, 2, 0)>(vb), h2 = tr_read<BOFF + v_rd_off(D0, 2, 1)>(vb), l3 = tr_read<BOFF + v_rd_off(D0, 3, 0)>(vb), h3 = tr_read<BOFF + v_rd_off(D0, 3, 1)>(vb);
;   asm volatile("s_waitcnt lgkmcnt(0)" ::: "memory"); SBAR();
;     ...
;   od = __builtin_amdgcn_mfma_f32_32x32x16_bf16(pa0, PK(l0, h0), od, 0, 0, 0);
;   od = __builtin_amdgcn_mfma_f32_32x32x16_bf16(pa1, PK(l1, h1), od, 0, 0, 0);
;   od = __builtin_amdgcn_mfma_f32_32x32x16_bf16(pa2, PK(l2, h2), od, 0, 0, 0);
;   od = __builtin_amdgcn_mfma_f32_32x32x16_bf16(pa3, PK(l3, h3), od, 0, 0, 0);
;     ...
; }
; template <int BOFF> __device__ __forceinline__ void pv_i(f32x16* o, int vb, bf16x8 pa0, bf16x8 pa1, bf16x8 pa2, bf16x8 pa3) {
;   pv_one_i<0, BOFF>(o[0], vb, pa0, pa1, pa2, pa3); pv_one_i<1, BOFF>(o[1], vb, pa0, pa1, pa2, pa3); pv_one_i<2, BOFF>(o[2], vb, pa0, pa1, pa2, pa3); pv_one_i<3, BOFF>(o[3], vb, pa0, pa1, pa2, pa3);
; }
	v_mfma_f32_32x32x16_bf16 v[0:15], v[100:103], v[184:187], v[0:15]
	ds_read_b64_tr_b16 v[184:185], v206 offset:0x5200
	ds_read_b64_tr_b16 v[186:187], v206 offset:0x5a00
	global_load_dwordx4 v[162:165], v[166:167], off
	s_nop 0
	global_load_dwordx4 v[166:169], v[166:167], off offset:-512
	s_nop 0
	global_load_dwordx4 v[174:177], v[170:171], off
	s_nop 0
	global_load_dwordx4 v[170:173], v[170:171], off offset:-512
	s_waitcnt lgkmcnt(7)
	v_mfma_f32_32x32x16_bf16 v[0:15], v[104:107], v[216:219], v[0:15]
	ds_read_b64_tr_b16 v[216:217], v206 offset:0x6200
	ds_read_b64_tr_b16 v[218:219], v206 offset:0x6a00
	s_waitcnt lgkmcnt(7)
	v_mfma_f32_32x32x16_bf16 v[0:15], v[108:111], v[220:223], v[0:15]
	ds_read_b64_tr_b16 v[220:221], v206 offset:0x7200
	ds_read_b64_tr_b16 v[222:223], v206 offset:0x7a00
	ds_write_b128 v212, v[158:161]
	s_waitcnt lgkmcnt(7)
	v_mfma_f32_32x32x16_bf16 v[16:31], v[96:99], v[180:183], v[16:31]
	ds_read_b64_tr_b16 v[180:181], v206 offset:0x4400
	ds_read_b64_tr_b16 v[182:183], v206 offset:0x4c00
	v_exp_f32_e32 v188, v72
	s_waitcnt lgkmcnt(7)
	v_mfma_f32_32x32x16_bf16 v[16:31], v[100:103], v[184:187], v[16:31]
	ds_read_b64_tr_b16 v[184:185], v206 offset:0x5400
	ds_read_b64_tr_b16 v[186:187], v206 offset:0x5c00
	v_exp_f32_e32 v189, v73
	s_waitcnt lgkmcnt(7)
	v_mfma_f32_32x32x16_bf16 v[16:31], v[104:107], v[216:219], v[16:31]
	ds_read_b64_tr_b16 v[216:217], v206 offset:0x6400
	ds_read_b64_tr_b16 v[218:219], v206 offset:0x6c00
	v_exp_f32_e32 v196, v74
	s_waitcnt lgkmcnt(7)
	v_mfma_f32_32x32x16_bf16 v[16:31], v[108:111], v[220:223], v[16:31]
	ds_read_b64_tr_b16 v[220:221], v206 offset:0x7400
	ds_read_b64_tr_b16 v[222:223], v206 offset:0x7c00
	v_exp_f32_e32 v197, v75
	ds_write_b128 v213, v[150:153]
	s_waitcnt lgkmcnt(7)
	v_mfma_f32_32x32x16_bf16 v[32:47], v[96:99], v[180:183], v[32:47]
	ds_read_b64_tr_b16 v[180:181], v206 offset:0x4600
	ds_read_b64_tr_b16 v[182:183], v206 offset:0x4e00
	v_exp_f32_e32 v198, v76
	s_waitcnt lgkmcnt(7)
	v_mfma_f32_32x32x16_bf16 v[32:47], v[100:103], v[184:187], v[32:47]
	ds_read_b64_tr_b16 v[184:185], v206 offset:0x5600
	ds_read_b64_tr_b16 v[186:187], v206 offset:0x5e00
	v_exp_f32_e32 v199, v77
	s_waitcnt lgkmcnt(7)
	v_mfma_f32_32x32x16_bf16 v[32:47], v[104:107], v[216:219], v[32:47]
	ds_read_b64_tr_b16 v[216:217], v206 offset:0x6600
	ds_read_b64_tr_b16 v[218:219], v206 offset:0x6e00
	s_waitcnt lgkmcnt(7)
	v_mfma_f32_32x32x16_bf16 v[32:47], v[108:111], v[220:223], v[32:47]
	ds_read_b64_tr_b16 v[220:221], v206 offset:0x7600
	ds_read_b64_tr_b16 v[222:223], v206 offset:0x7e00
	ds_write_b128 v214, v[154:157]
	s_waitcnt lgkmcnt(7)
	v_mfma_f32_32x32x16_bf16 v[48:63], v[96:99], v[180:183], v[48:63]
	s_waitcnt vmcnt(4)
	v_exp_f32_e32 v180, v64
	v_exp_f32_e32 v181, v65
	v_exp_f32_e32 v182, v66
	v_exp_f32_e32 v183, v67
	s_waitcnt lgkmcnt(5)
	v_mfma_f32_32x32x16_bf16 v[48:63], v[100:103], v[184:187], v[48:63]
	v_exp_f32_e32 v184, v68
	v_exp_f32_e32 v185, v69
	v_exp_f32_e32 v186, v70
	v_exp_f32_e32 v187, v71
	s_waitcnt lgkmcnt(3)
	v_mfma_f32_32x32x16_bf16 v[48:63], v[104:107], v[216:219], v[48:63]
	v_exp_f32_e32 v216, v78
	v_exp_f32_e32 v217, v79
	s_waitcnt lgkmcnt(0)
	s_barrier
	v_mfma_f32_32x32x16_bf16 v[48:63], v[108:111], v[220:223], v[48:63]
	ds_read_b128 v[64:67], v207
	ds_read_b128 v[68:71], v207 offset:8192
	ds_read_b128 v[146:149], v208
	ds_read_b128 v[150:153], v208 offset:8192
	v_exp_f32_e32 v154, v88
	v_exp_f32_e32 v155, v89
	v_exp_f32_e32 v156, v90
	v_exp_f32_e32 v157, v91
	v_exp_f32_e32 v158, v92
	v_exp_f32_e32 v159, v93
	v_exp_f32_e32 v160, v94
	v_exp_f32_e32 v95, v95
	s_waitcnt lgkmcnt(3)
	v_mfma_f32_32x32x16_bf16 v[96:111], v[64:67], v[142:145], 0
	v_exp_f32_e32 v236, v80
	v_add_f32_e32 v80, 0, v180
	v_add_f32_e32 v80, v181, v80
	v_add_f32_e32 v80, v182, v80
	s_waitcnt lgkmcnt(2)
	v_mfma_f32_32x32x16_bf16 v[64:79], v[68:71], v[142:145], 0
	v_add_f32_e32 v80, v183, v80
	v_add_f32_e32 v80, v184, v80
	v_add_f32_e32 v80, v185, v80
	s_waitcnt lgkmcnt(1)
	v_mfma_f32_32x32x16_bf16 v[96:111], v[146:149], v[138:141], v[96:111]
	v_add_f32_e32 v80, v186, v80
	v_add_f32_e32 v80, v187, v80
	v_add_f32_e32 v80, v188, v80
	s_waitcnt lgkmcnt(0)
	v_mfma_f32_32x32x16_bf16 v[64:79], v[150:153], v[138:141], v[64:79]
	ds_read_b128 v[146:149], v209
	ds_read_b128 v[150:153], v209 offset:8192
	v_add_f32_e32 v80, v189, v80
	v_add_f32_e32 v80, v196, v80
	v_add_f32_e32 v80, v197, v80
	v_add_f32_e32 v80, v198, v80
	v_exp_f32_e32 v237, v81
	s_waitcnt lgkmcnt(1)
	v_mfma_f32_32x32x16_bf16 v[96:111], v[146:149], v[112:115], v[96:111]
	v_add_f32_e32 v80, v199, v80
	v_exp_f32_e32 v238, v82
	v_add_f32_e32 v80, v216, v80
	v_exp_f32_e32 v239, v83
	s_waitcnt lgkmcnt(0)
	v_mfma_f32_32x32x16_bf16 v[64:79], v[150:153], v[112:115], v[64:79]
	ds_read_b128 v[146:149], v210
	ds_read_b128 v[150:153], v210 offset:8192
	v_add_f32_e32 v80, v217, v80
	v_exp_f32_e32 v247, v84
	v_add_f32_e32 v80, v236, v80
	v_exp_f32_e32 v248, v85
	s_waitcnt lgkmcnt(1)
	v_mfma_f32_32x32x16_bf16 v[96:111], v[146:149], v[116:119], v[96:111]
	v_add_f32_e32 v80, v237, v80
	v_exp_f32_e32 v249, v86
	v_add_f32_e32 v80, v238, v80
	v_exp_f32_e32 v252, v87
	s_waitcnt lgkmcnt(0)
	v_mfma_f32_32x32x16_bf16 v[64:79], v[150:153], v[116:119], v[64:79]
	ds_read_b128 v[146:149], v190 offset:0
	ds_read_b128 v[150:153], v190 offset:8192
	v_add_f32_e32 v80, v239, v80
	v_add_f32_e32 v80, v247, v80
	v_add_f32_e32 v80, v248, v80
	v_add_f32_e32 v80, v249, v80
	v_add_f32_e32 v80, v252, v80
	v_add_f32_e32 v80, v154, v80
	s_waitcnt lgkmcnt(1)
	v_mfma_f32_32x32x16_bf16 v[96:111], v[146:149], v[120:123], v[96:111]
	v_add_f32_e32 v80, v155, v80
	v_add_f32_e32 v80, v156, v80
	v_add_f32_e32 v80, v157, v80
	v_add_f32_e32 v80, v158, v80
	v_add_f32_e32 v80, v159, v80
	s_waitcnt lgkmcnt(0)
; #define SBAR() __builtin_amdgcn_sched_barrier(0)
; __device__ __forceinline__ void finishSM(f32x16& p0, f32x16& p1, float alpha, float& l_reg, bf16x8& pa0, bf16x8& pa1, bf16x8& pa2, bf16x8& pa3) {
;   for (int r = 0; r < 16; ++r) p1[r] = __builtin_amdgcn_exp2f(p1[r]);
;   float ps = 0; for (int r = 0; r < 16; ++r) ps += p0[r]; for (int r = 0; r < 16; ++r) ps += p1[r];
;   { auto rr = __builtin_amdgcn_permlane32_swap(__float_as_uint(ps), __float_as_uint(ps), false, false);
;     ps = __uint_as_float(rr[0]) + __uint_as_float(rr[1]); }
;   l_reg = l_reg * alpha + ps;
;     ...
;   PK4(p0, 0, pa0); PK4(p0, 8, pa1); PK4(p1, 0, pa2); PK4(p1, 8, pa3);
;     ...
; }
; template <int D0, int BOFF> __device__ __forceinline__ void pv_one_i(f32x16& od, int vb, bf16x8 pa0, bf16x8 pa1, bf16x8 pa2, bf16x8 pa3) {
;   const s16x4 l0 = tr_read<BOFF + v_rd_off(D0, 0, 0)>(vb), h0 = tr_read<BOFF + v_rd_off(D0, 0, 1)>(vb), l1 = tr_read<BOFF + v_rd_off(D0, 1, 0)>(vb), h1 = tr_read<BOFF + v_rd_off(D0, 1, 1)>(vb);
;   const s16x4 l2 = tr_read<BOFF + v_rd_off(D0, 2, 0)>(vb), h2 = tr_read<BOFF + v_rd_off(D0, 2, 1)>(vb), l3 = tr_read<BOFF + v_rd_off(D0, 3, 0)>(vb), h3 = tr_read<BOFF + v_rd_off(D0, 3, 1)>(vb);
;   asm volatile("s_waitcnt lgkmcnt(0)" ::: "memory"); SBAR();
;     ...
;   od = __builtin_amdgcn_mfma_f32_32x32x16_bf16(pa0, PK(l0, h0), od, 0, 0, 0);
;   od = __builtin_amdgcn_mfma_f32_32x32x16_bf16(pa1, PK(l1, h1), od, 0, 0, 0);
;   od = __builtin_amdgcn_mfma_f32_32x32x16_bf16(pa2, PK(l2, h2), od, 0, 0, 0);
;   od = __builtin_amdgcn_mfma_f32_32x32x16_bf16(pa3, PK(l3, h3), od, 0, 0, 0);
;     ...
; }
; template <int BOFF> __device__ __forceinline__ void pv_i(f32x16* o, int vb, bf16x8 pa0, bf16x8 pa1, bf16x8 pa2, bf16x8 pa3) {
;   pv_one_i<0, BOFF>(o[0], vb, pa0, pa1, pa2, pa3); pv_one_i<1, BOFF>(o[1], vb, pa0, pa1, pa2, pa3); pv_one_i<2, BOFF>(o[2], vb, pa0, pa1, pa2, pa3); pv_one_i<3, BOFF>(o[3], vb, pa0, pa1, pa2, pa3);
; }
	v_mfma_f32_32x32x16_bf16 v[64:79], v[150:153], v[120:123], v[64:79]
	ds_read_b128 v[146:149], v191 offset:0
	ds_read_b128 v[150:153], v191 offset:8192
	v_add_f32_e32 v80, v160, v80
	v_add_f32_e32 v80, v95, v80
	v_mov_b32_e32 v81, v80
	s_nop 1
	v_permlane32_swap_b32_e32 v80, v81
	v_add_f32_e32 v80, v80, v81
	s_waitcnt lgkmcnt(1)
	v_mfma_f32_32x32x16_bf16 v[96:111], v[146:149], v[124:127], v[96:111]
	v_add_f32_e32 v215, v128, v80
	v_cvt_pk_bf16_f32 v80, v180, v181
	v_cvt_pk_bf16_f32 v81, v182, v183
	v_cvt_pk_bf16_f32 v82, v184, v185
	v_cvt_pk_bf16_f32 v83, v186, v187
	s_waitcnt lgkmcnt(0)
	v_mfma_f32_32x32x16_bf16 v[64:79], v[150:153], v[124:127], v[64:79]
	ds_read_b128 v[146:149], v192 offset:0
	ds_read_b128 v[150:153], v192 offset:8192
	v_cvt_pk_bf16_f32 v84, v188, v189
	v_cvt_pk_bf16_f32 v85, v196, v197
	v_cvt_pk_bf16_f32 v86, v198, v199
	v_cvt_pk_bf16_f32 v87, v216, v217
	v_cvt_pk_bf16_f32 v88, v236, v237
	v_cvt_pk_bf16_f32 v89, v238, v239
	s_waitcnt lgkmcnt(1)
	v_mfma_f32_32x32x16_bf16 v[96:111], v[146:149], v[130:133], v[96:111]
	v_cvt_pk_bf16_f32 v90, v247, v248
	v_cvt_pk_bf16_f32 v91, v249, v252
	v_cvt_pk_bf16_f32 v92, v154, v155
	v_cvt_pk_bf16_f32 v93, v156, v157
	v_cvt_pk_bf16_f32 v94, v158, v159
	s_waitcnt lgkmcnt(0)
	v_mfma_f32_32x32x16_bf16 v[64:79], v[150:153], v[130:133], v[64:79]
	ds_read_b128 v[146:149], v193 offset:0
	ds_read_b128 v[150:153], v193 offset:8192
	ds_read_b64_tr_b16 v[180:181], v206 offset:0x8000
	ds_read_b64_tr_b16 v[182:183], v206 offset:0x8800
	ds_read_b64_tr_b16 v[184:185], v206 offset:0x9000
	ds_read_b64_tr_b16 v[186:187], v206 offset:0x9800
	ds_read_b64_tr_b16 v[216:217], v206 offset:0xa000
	ds_read_b64_tr_b16 v[218:219], v206 offset:0xa800
	ds_read_b64_tr_b16 v[220:221], v206 offset:0xb000
	ds_read_b64_tr_b16 v[222:223], v206 offset:0xb800
	v_cvt_pk_bf16_f32 v95, v160, v95
	s_nop 0
	v_permlane32_swap_b32_e32 v80, v82
	v_permlane32_swap_b32_e32 v81, v83
	v_permlane32_swap_b32_e32 v84, v86
	v_permlane32_swap_b32_e32 v85, v87
	s_waitcnt lgkmcnt(9)
	v_mfma_f32_32x32x16_bf16 v[96:111], v[146:149], v[134:137], v[96:111]
	v_permlane32_swap_b32_e32 v88, v90
	v_permlane32_swap_b32_e32 v89, v91
	v_permlane32_swap_b32_e32 v92, v94
	v_permlane32_swap_b32_e32 v93, v95
	s_waitcnt lgkmcnt(8)
	v_mfma_f32_32x32x16_bf16 v[64:79], v[150:153], v[134:137], v[64:79]
	s_waitcnt vmcnt(0)
	ds_write_b128 v211, v[162:165] offset:16384
	s_nop 0
	s_waitcnt lgkmcnt(7)
	v_mfma_f32_32x32x16_bf16 v[0:15], v[80:83], v[180:183], v[0:15]
	ds_read_b64_tr_b16 v[180:181], v206 offset:0x8200
	ds_read_b64_tr_b16 v[182:183], v206 offset:0x8a00
	v_add_co_u32_e32 v150, vcc, s58, v178
	s_nop 1
	v_addc_co_u32_e32 v151, vcc, -1, v179, vcc
	s_waitcnt lgkmcnt(7)
	v_mfma_f32_32x32x16_bf16 v[0:15], v[84:87], v[184:187], v[0:15]
	ds_read_b64_tr_b16 v[184:185], v206 offset:0x9200
	ds_read_b64_tr_b16 v[186:187], v206 offset:0x9a00
	global_load_dwordx4 v[146:149], v[150:151], off
	global_load_dwordx4 v[154:157], v[150:151], off offset:-512
	s_nop 0
	global_load_dwordx4 v[150:153], v[178:179], off
	global_load_dwordx4 v[158:161], v[178:179], off offset:-512
	s_waitcnt lgkmcnt(7)
	v_mfma_f32_32x32x16_bf16 v[0:15], v[88:91], v[216:219], v[0:15]
	ds_read_b64_tr_b16 v[216:217], v206 offset:0xa200
	ds_read_b64_tr_b16 v[218:219], v206 offset:0xaa00
	s_waitcnt lgkmcnt(7)
	v_mfma_f32_32x32x16_bf16 v[0:15], v[92:95], v[220:223], v[0:15]
	ds_read_b64_tr_b16 v[220:221], v206 offset:0xb200
	ds_read_b64_tr_b16 v[222:223], v206 offset:0xba00
	ds_write_b128 v212, v[174:177] offset:16384
	s_waitcnt lgkmcnt(7)
	v_mfma_f32_32x32x16_bf16 v[16:31], v[80:83], v[180:183], v[16:31]
	ds_read_b64_tr_b16 v[180:181], v206 offset:0x8400
	ds_read_b64_tr_b16 v[182:183], v206 offset:0x8c00
	v_exp_f32_e32 v229, v96
	s_waitcnt lgkmcnt(7)
	v_mfma_f32_32x32x16_bf16 v[16:31], v[84:87], v[184:187], v[16:31]
	ds_read_b64_tr_b16 v[184:185], v206 offset:0x9400
	ds_read_b64_tr_b16 v[186:187], v206 offset:0x9c00
	v_exp_f32_e32 v243, v97
	s_waitcnt lgkmcnt(7)
	v_mfma_f32_32x32x16_bf16 v[16:31], v[88:91], v[216:219], v[16:31]
	ds_read_b64_tr_b16 v[216:217], v206 offset:0xa400
	ds_read_b64_tr_b16 v[218:219], v206 offset:0xac00
	v_exp_f32_e32 v244, v98
	s_waitcnt lgkmcnt(7)
	v_mfma_f32_32x32x16_bf16 v[16:31], v[92:95], v[220:223], v[16:31]
	ds_read_b64_tr_b16 v[220:221], v206 offset:0xb400
	ds_read_b64_tr_b16 v[222:223], v206 offset:0xbc00
	v_exp_f32_e32 v246, v99
	ds_write_b128 v213, v[166:169] offset:16384
	s_waitcnt lgkmcnt(7)
	v_mfma_f32_32x32x16_bf16 v[32:47], v[80:83], v[180:183], v[32:47]
	ds_read_b64_tr_b16 v[180:181], v206 offset:0x8600
	ds_read_b64_tr_b16 v[182:183], v206 offset:0x8e00
	v_exp_f32_e32 v242, v100
	s_waitcnt lgkmcnt(7)
	v_mfma_f32_32x32x16_bf16 v[32:47], v[84:87], v[184:187], v[32:47]
	ds_read_b64_tr_b16 v[184:185], v206 offset:0x9600
	ds_read_b64_tr_b16 v[186:187], v206 offset:0x9e00
	v_exp_f32_e32 v245, v101
	s_waitcnt lgkmcnt(7)
	v_mfma_f32_32x32x16_bf16 v[32:47], v[88:91], v[216:219], v[32:47]
	ds_read_b64_tr_b16 v[216:217], v206 offset:0xa600
	ds_read_b64_tr_b16 v[218:219], v206 offset:0xae00
	v_exp_f32_e32 v227, v102
	s_waitcnt lgkmcnt(7)
	v_mfma_f32_32x32x16_bf16 v[32:47], v[92:95], v[220:223], v[32:47]
	ds_read_b64_tr_b16 v[220:221], v206 offset:0xb600
	ds_read_b64_tr_b16 v[222:223], v206 offset:0xbe00
	v_exp_f32_e32 v228, v103
	ds_write_b128 v214, v[170:173] offset:16384
	s_waitcnt lgkmcnt(7)
	v_mfma_f32_32x32x16_bf16 v[48:63], v[80:83], v[180:183], v[48:63]
	s_waitcnt lgkmcnt(5)
	v_mfma_f32_32x32x16_bf16 v[48:63], v[84:87], v[184:187], v[48:63]
	v_exp_f32_e32 v226, v105
	v_exp_f32_e32 v224, v106
	v_exp_f32_e32 v225, v107
	s_waitcnt vmcnt(4)
	s_add_i32 s28, s28, 6
	v_lshl_add_u64 v[178:179], v[178:179], 0, s[60:61]
	s_waitcnt lgkmcnt(3)
	v_mfma_f32_32x32x16_bf16 v[48:63], v[88:91], v[216:219], v[48:63]
	v_exp_f32_e32 v219, v110
	s_cmpk_lt_u32 s28, 0x75
	s_waitcnt lgkmcnt(1)
	v_mfma_f32_32x32x16_bf16 v[48:63], v[92:95], v[220:223], v[48:63]
	v_exp_f32_e32 v223, v104
	v_exp_f32_e32 v220, v108
	v_exp_f32_e32 v222, v109
	v_exp_f32_e32 v221, v111
	s_cbranch_scc1 .LBB0_352
; #define SWRITE_I(B, i) do { LDSV(wv0 + (B) * 16384) = sr_[i].vs0; LDSV(wv1 + (B) * 16384) = sr_[i].vs1; LDSV(wk0 + (B) * 16384) = sr_[i].ks0; LDSV(wk1 + (B) * 16384) = sr_[i].ks1; } while (0)
; #define NOP_() do { } while (0)
; __device__ __forceinline__ void finishSM(f32x16& p0, f32x16& p1, float alpha, float& l_reg, bf16x8& pa0, bf16x8& pa1, bf16x8& pa2, bf16x8& pa3) {
;   for (int r = 0; r < 16; ++r) p1[r] = __builtin_amdgcn_exp2f(p1[r]);
;   float ps = 0; for (int r = 0; r < 16; ++r) ps += p0[r]; for (int r = 0; r < 16; ++r) ps += p1[r];
;   { auto rr = __builtin_amdgcn_permlane32_swap(__float_as_uint(ps), __float_as_uint(ps), false, false);
;     ps = __uint_as_float(rr[0]) + __uint_as_float(rr[1]); }
;   l_reg = l_reg * alpha + ps;
;     ...
;   PK4(p0, 0, pa0); PK4(p0, 8, pa1); PK4(p1, 0, pa2); PK4(p1, 8, pa3);
;     ...
; }
; template <bool PARTIAL, bool FIXED> ...
;     ...
;   if constexpr (!PARTIAL) { const int i1 = tid & 255;
;     warm0 = *(const unsigned*)(Qb_n + (long)(tid >> 1) * LDQ + (tid & 1) * 64);
;     warm1 = *(const unsigned*)((tid < 256 ? Kh_n : Vh_n) + (long)(i1 >> 1) * LDK + (i1 & 1) * 64); }
;   HALF_B(1, 0, NOP_(), SWRITE_I(2, 0));
	v_mov_b32_e32 v252, 0x7fc00000
	v_readlane_b32 s8, v255, 42
	v_readlane_b32 s9, v255, 43
	s_add_u32 s2, s8, s6
	s_addc_u32 s3, s9, s7
	s_lshl_b32 s4, s65, 1
	s_add_u32 s2, s2, s4
	s_addc_u32 s3, s3, 0
	v_ashrrev_i32_e32 v82, 1, v195
	v_mov_b64_e32 v[80:81], s[2:3]
	v_mad_i64_i32 v[80:81], s[2:3], v82, s17, v[80:81]
	v_lshlrev_b32_e32 v82, 7, v195
	v_and_b32_e32 v128, 0x80, v82
	v_lshl_add_u64 v[80:81], v[80:81], 0, v[128:129]
	s_add_u32 s4, s8, s64
	global_load_dword v216, v[80:81], off
	v_cmp_gt_i32_e32 vcc, s14, v195
	v_mov_b32_e32 v80, 0xa00
	v_mov_b32_e32 v81, 0x800
	s_addc_u32 s5, s9, s57
	v_cndmask_b32_e32 v80, v80, v81, vcc
	v_mov_b32_e32 v81, v129
	v_bfe_u32 v82, v195, 1, 7
	v_lshl_add_u64 v[80:81], s[4:5], 0, v[80:81]
	s_lshl_b32 s46, s56, 1
	v_mul_u32_u24_e32 v82, 0x600, v82
	v_lshl_add_u64 v[80:81], v[80:81], 0, s[46:47]
	v_lshlrev_b32_e32 v82, 1, v82
	v_mov_b32_e32 v83, v129
	v_lshl_add_u64 v[80:81], v[80:81], 0, v[82:83]
	v_lshl_add_u64 v[80:81], v[80:81], 0, v[128:129]
	global_load_dword v217, v[80:81], off
	v_and_b32_e32 v247, 0x3fffffc0, v195
	s_waitcnt lgkmcnt(0)
	s_barrier
	ds_read_b128 v[80:83], v207 offset:16384
	ds_read_b128 v[96:99], v207 offset:24576
	ds_read_b128 v[100:103], v208 offset:16384
	ds_read_b128 v[170:173], v208 offset:24576
	v_exp_f32_e32 v104, v68
	v_exp_f32_e32 v105, v69
	s_waitcnt lgkmcnt(3)
	v_mfma_f32_32x32x16_bf16 v[80:95], v[80:83], v[142:145], 0
	v_exp_f32_e32 v106, v70
	v_exp_f32_e32 v107, v71
	v_exp_f32_e32 v108, v72
	v_exp_f32_e32 v109, v73
	v_exp_f32_e32 v110, v74
	v_exp_f32_e32 v111, v75
	v_exp_f32_e32 v196, v76
	s_waitcnt lgkmcnt(1)
	v_mfma_f32_32x32x16_bf16 v[80:95], v[100:103], v[138:141], v[80:95]
	ds_read_b128 v[100:103], v209 offset:16384
	ds_read_b128 v[162:165], v209 offset:24576
	v_exp_f32_e32 v197, v77
	v_exp_f32_e32 v198, v78
	v_exp_f32_e32 v79, v79
	s_waitcnt lgkmcnt(1)
	v_mfma_f32_32x32x16_bf16 v[80:95], v[100:103], v[112:115], v[80:95]
	ds_read_b128 v[100:103], v210 offset:16384
	ds_read_b128 v[166:169], v210 offset:24576
	s_waitcnt lgkmcnt(1)
	v_mfma_f32_32x32x16_bf16 v[80:95], v[100:103], v[116:119], v[80:95]
	ds_read_b128 v[100:103], v190 offset:16384
	ds_read_b128 v[174:177], v190 offset:24576
	s_waitcnt lgkmcnt(1)
	v_mfma_f32_32x32x16_bf16 v[80:95], v[100:103], v[120:123], v[80:95]
	ds_read_b128 v[100:103], v191 offset:16384
	ds_read_b128 v[178:181], v191 offset:24576
	s_waitcnt lgkmcnt(1)
	v_mfma_f32_32x32x16_bf16 v[80:95], v[100:103], v[124:127], v[80:95]
	ds_read_b128 v[100:103], v192 offset:16384
	ds_read_b128 v[182:185], v192 offset:24576
	s_waitcnt lgkmcnt(1)
	v_mfma_f32_32x32x16_bf16 v[80:95], v[100:103], v[130:133], v[80:95]
	ds_read_b128 v[100:103], v193 offset:16384
	ds_read_b128 v[186:189], v193 offset:24576
	s_waitcnt lgkmcnt(1)
	v_mfma_f32_32x32x16_bf16 v[80:95], v[100:103], v[134:137], v[80:95]
	v_exp_f32_e32 v100, v64
	v_add_f32_e32 v64, 0, v229
	v_add_f32_e32 v64, v243, v64
	v_add_f32_e32 v64, v244, v64
	v_add_f32_e32 v64, v246, v64
	v_add_f32_e32 v64, v242, v64
	v_add_f32_e32 v64, v245, v64
	v_add_f32_e32 v64, v227, v64
	v_add_f32_e32 v64, v228, v64
	v_add_f32_e32 v64, v223, v64
	v_add_f32_e32 v64, v226, v64
	v_add_f32_e32 v64, v224, v64
	v_add_f32_e32 v64, v225, v64
	v_add_f32_e32 v64, v220, v64
	v_exp_f32_e32 v101, v65
	v_add_f32_e32 v64, v222, v64
	v_exp_f32_e32 v102, v66
	v_add_f32_e32 v64, v219, v64
	v_exp_f32_e32 v103, v67
	v_add_f32_e32 v64, v221, v64
	v_add_f32_e32 v64, v100, v64
	v_add_f32_e32 v64, v101, v64
	v_add_f32_e32 v64, v102, v64
	v_add_f32_e32 v64, v103, v64
	v_add_f32_e32 v64, v104, v64
	v_add_f32_e32 v64, v105, v64
	v_add_f32_e32 v64, v106, v64
	v_add_f32_e32 v64, v107, v64
	v_add_f32_e32 v64, v108, v64
	v_add_f32_e32 v64, v109, v64
	v_add_f32_e32 v64, v110, v64
	v_add_f32_e32 v64, v111, v64
	v_add_f32_e32 v64, v196, v64
	v_add_f32_e32 v64, v197, v64
	v_add_f32_e32 v64, v198, v64
	v_add_f32_e32 v128, v79, v64
	v_mov_b32_e32 v218, v128
	s_nop 1
	v_permlane32_swap_b32_e32 v128, v218
	v_cvt_pk_bf16_f32 v64, v229, v243
	v_cvt_pk_bf16_f32 v65, v244, v246
	v_cvt_pk_bf16_f32 v66, v242, v245
	v_cvt_pk_bf16_f32 v67, v227, v228
	v_cvt_pk_bf16_f32 v68, v223, v226
	v_cvt_pk_bf16_f32 v69, v224, v225
	v_cvt_pk_bf16_f32 v70, v220, v222
	v_cvt_pk_bf16_f32 v71, v219, v221
	v_cvt_pk_bf16_f32 v72, v100, v101
	v_cvt_pk_bf16_f32 v73, v102, v103
	v_cvt_pk_bf16_f32 v74, v104, v105
	v_cvt_pk_bf16_f32 v75, v106, v107
	v_cvt_pk_bf16_f32 v76, v108, v109
	v_cvt_pk_bf16_f32 v77, v110, v111
	v_cvt_pk_bf16_f32 v78, v196, v197
	v_cvt_pk_bf16_f32 v79, v198, v79
	s_nop 0
	v_permlane32_swap_b32_e32 v64, v66
	v_permlane32_swap_b32_e32 v65, v67
	v_permlane32_swap_b32_e32 v68, v70
	v_permlane32_swap_b32_e32 v69, v71
	v_permlane32_swap_b32_e32 v72, v74
	v_permlane32_swap_b32_e32 v73, v75
	v_permlane32_swap_b32_e32 v76, v78
	v_permlane32_swap_b32_e32 v77, v79
	ds_read_b64_tr_b16 v[100:101], v206 offset:0
	ds_read_b64_tr_b16 v[102:103], v206 offset:0x800
	ds_read_b64_tr_b16 v[104:105], v206 offset:0x1000
	ds_read_b64_tr_b16 v[106:107], v206 offset:0x1800
	ds_read_b64_tr_b16 v[108:109], v206 offset:0x2000
	ds_read_b64_tr_b16 v[110:111], v206 offset:0x2800
	ds_read_b64_tr_b16 v[220:221], v206 offset:0x3000
	ds_read_b64_tr_b16 v[222:223], v206 offset:0x3800
	s_waitcnt lgkmcnt(0)
	s_nop 0
	v_mfma_f32_32x32x16_bf16 v[0:15], v[64:67], v[100:103], v[0:15]
	ds_read_b64_tr_b16 v[100:101], v206 offset:0x200
	ds_read_b64_tr_b16 v[102:103], v206 offset:0xa00
	v_mfma_f32_32x32x16_bf16 v[0:15], v[68:71], v[104:107], v[0:15]
	ds_read_b64_tr_b16 v[104:105], v206 offset:0x1200
	ds_read_b64_tr_b16 v[106:107], v206 offset:0x1a00
	v_mfma_f32_32x32x16_bf16 v[0:15], v[72:75], v[108:111], v[0:15]
	ds_read_b64_tr_b16 v[108:109], v206 offset:0x2200
	ds_read_b64_tr_b16 v[110:111], v206 offset:0x2a00
	v_mfma_f32_32x32x16_bf16 v[0:15], v[76:79], v[220:223], v[0:15]
	ds_read_b64_tr_b16 v[220:221], v206 offset:0x3200
	ds_read_b64_tr_b16 v[222:223], v206 offset:0x3a00
	s_waitcnt lgkmcnt(0)
; #define SBAR() __builtin_amdgcn_sched_barrier(0)
; template <int BOFF> __device__ __forceinline__ void qkt_i(f32x16& p0, f32x16& p1, const int (&kb)[4], const bf16x8* qr) {
;   p0 = f32x16{}; p1 = f32x16{};
; #pragma unroll
;   for (int d0 = 0; d0 < 8; ++d0) { const int off = BOFF + (d0 >> 2) * 128;
;     const bf16x8 b0 = LDSV(kb[d0 & 3] + off), b1 = LDSV(kb[d0 & 3] + off + 8192);
;     p0 = __builtin_amdgcn_mfma_f32_32x32x16_bf16(b0, qr[d0], p0, 0, 0, 0);
;     p1 = __builtin_amdgcn_mfma_f32_32x32x16_bf16(b1, qr[d0], p1, 0, 0, 0); }
; }
; template <int D0, int BOFF> __device__ __forceinline__ void pv_one_i(f32x16& od, int vb, bf16x8 pa0, bf16x8 pa1, bf16x8 pa2, bf16x8 pa3) {
;   const s16x4 l0 = tr_read<BOFF + v_rd_off(D0, 0, 0)>(vb), h0 = tr_read<BOFF + v_rd_off(D0, 0, 1)>(vb), l1 = tr_read<BOFF + v_rd_off(D0, 1, 0)>(vb), h1 = tr_read<BOFF + v_rd_off(D0, 1, 1)>(vb);
;   const s16x4 l2 = tr_read<BOFF + v_rd_off(D0, 2, 0)>(vb), h2 = tr_read<BOFF + v_rd_off(D0, 2, 1)>(vb), l3 = tr_read<BOFF + v_rd_off(D0, 3, 0)>(vb), h3 = tr_read<BOFF + v_rd_off(D0, 3, 1)>(vb);
;   asm volatile("s_waitcnt lgkmcnt(0)" ::: "memory"); SBAR();
;     ...
;   od = __builtin_amdgcn_mfma_f32_32x32x16_bf16(pa0, PK(l0, h0), od, 0, 0, 0);
;   od = __builtin_amdgcn_mfma_f32_32x32x16_bf16(pa1, PK(l1, h1), od, 0, 0, 0);
;   od = __builtin_amdgcn_mfma_f32_32x32x16_bf16(pa2, PK(l2, h2), od, 0, 0, 0);
;   od = __builtin_amdgcn_mfma_f32_32x32x16_bf16(pa3, PK(l3, h3), od, 0, 0, 0);
;     ...
; }
; template <int BOFF> __device__ __forceinline__ void pv_i(f32x16* o, int vb, bf16x8 pa0, bf16x8 pa1, bf16x8 pa2, bf16x8 pa3) {
;   pv_one_i<0, BOFF>(o[0], vb, pa0, pa1, pa2, pa3); pv_one_i<1, BOFF>(o[1], vb, pa0, pa1, pa2, pa3); pv_one_i<2, BOFF>(o[2], vb, pa0, pa1, pa2, pa3); pv_one_i<3, BOFF>(o[3], vb, pa0, pa1, pa2, pa3);
; }
	v_mfma_f32_32x32x16_bf16 v[16:31], v[64:67], v[100:103], v[16:31]
	ds_read_b64_tr_b16 v[100:101], v206 offset:0x400
	ds_read_b64_tr_b16 v[102:103], v206 offset:0xc00
	v_mfma_f32_32x32x16_bf16 v[16:31], v[68:71], v[104:107], v[16:31]
	ds_read_b64_tr_b16 v[104:105], v206 offset:0x1400
	ds_read_b64_tr_b16 v[106:107], v206 offset:0x1c00
	v_mfma_f32_32x32x16_bf16 v[16:31], v[72:75], v[108:111], v[16:31]
	ds_read_b64_tr_b16 v[108:109], v206 offset:0x2400
	ds_read_b64_tr_b16 v[110:111], v206 offset:0x2c00
	v_mfma_f32_32x32x16_bf16 v[16:31], v[76:79], v[220:223], v[16:31]
	ds_read_b64_tr_b16 v[220:221], v206 offset:0x3400
	ds_read_b64_tr_b16 v[222:223], v206 offset:0x3c00
	s_waitcnt lgkmcnt(0)
	v_mfma_f32_32x32x16_bf16 v[32:47], v[64:67], v[100:103], v[32:47]
	ds_read_b64_tr_b16 v[100:101], v206 offset:0x600
	ds_read_b64_tr_b16 v[102:103], v206 offset:0xe00
	v_mfma_f32_32x32x16_bf16 v[32:47], v[68:71], v[104:107], v[32:47]
	ds_read_b64_tr_b16 v[104:105], v206 offset:0x1600
	ds_read_b64_tr_b16 v[106:107], v206 offset:0x1e00
	v_mfma_f32_32x32x16_bf16 v[32:47], v[72:75], v[108:111], v[32:47]
	ds_read_b64_tr_b16 v[108:109], v206 offset:0x2600
	ds_read_b64_tr_b16 v[110:111], v206 offset:0x2e00
	v_mfma_f32_32x32x16_bf16 v[32:47], v[76:79], v[220:223], v[32:47]
	ds_read_b64_tr_b16 v[220:221], v206 offset:0x3600
	ds_read_b64_tr_b16 v[222:223], v206 offset:0x3e00
	s_waitcnt lgkmcnt(0)
	v_mfma_f32_32x32x16_bf16 v[48:63], v[64:67], v[100:103], v[48:63]
	s_waitcnt vmcnt(5)
	ds_write_b128 v211, v[146:149] offset:32768
	s_waitcnt vmcnt(3)
	ds_write_b128 v212, v[150:153] offset:32768
	ds_write_b128 v213, v[154:157] offset:32768
	s_waitcnt vmcnt(2)
	ds_write_b128 v214, v[158:161] offset:32768
	s_waitcnt lgkmcnt(0)
	s_barrier
	v_mfma_f32_32x32x16_bf16 v[48:63], v[68:71], v[104:107], v[48:63]
	v_mfma_f32_32x32x16_bf16 v[48:63], v[72:75], v[108:111], v[48:63]
	v_mfma_f32_32x32x16_bf16 v[48:63], v[76:79], v[220:223], v[48:63]
	ds_read_b128 v[64:67], v207 offset:32768
	ds_read_b128 v[100:103], v208 offset:32768
	s_add_i32 s2, 0, 0x18000
	s_waitcnt lgkmcnt(1)
	v_mfma_f32_32x32x16_bf16 v[64:79], v[64:67], v[142:145], 0
	s_waitcnt lgkmcnt(0)
	v_mfma_f32_32x32x16_bf16 v[64:79], v[100:103], v[138:141], v[64:79]
	ds_read_b128 v[100:103], v209 offset:32768
	s_waitcnt lgkmcnt(0)
	v_mfma_f32_32x32x16_bf16 v[64:79], v[100:103], v[112:115], v[64:79]
	ds_read_b128 v[100:103], v210 offset:32768
	s_waitcnt lgkmcnt(0)
	v_mfma_f32_32x32x16_bf16 v[64:79], v[100:103], v[116:119], v[64:79]
	ds_read_b128 v[100:103], v190 offset:32768
	s_waitcnt lgkmcnt(0)
	v_mfma_f32_32x32x16_bf16 v[64:79], v[100:103], v[120:123], v[64:79]
	ds_read_b128 v[100:103], v191 offset:32768
	s_waitcnt lgkmcnt(0)
	v_mfma_f32_32x32x16_bf16 v[64:79], v[100:103], v[124:127], v[64:79]
	ds_read_b128 v[100:103], v192 offset:32768
	s_waitcnt lgkmcnt(0)
	v_mfma_f32_32x32x16_bf16 v[64:79], v[100:103], v[130:133], v[64:79]
	ds_read_b128 v[100:103], v193 offset:32768
	s_waitcnt lgkmcnt(0)
	v_and_b32_e32 v190, 63, v195
	v_lshlrev_b32_e32 v191, 4, v195
	v_and_b32_e32 v192, 31, v195
	v_bfe_u32 v193, v195, 5, 1
	v_mfma_f32_32x32x16_bf16 v[64:79], v[100:103], v[134:137], v[64:79]
	v_mfma_f32_32x32x16_bf16 v[96:111], v[96:99], v[142:145], 0
	s_nop 10
	v_exp_f32_e32 v72, v80
	v_exp_f32_e32 v80, v81
	v_exp_f32_e32 v73, v82
	v_exp_f32_e32 v81, v83
	v_exp_f32_e32 v74, v84
	v_add_f32_e32 v84, 0, v72
	v_exp_f32_e32 v82, v85
	v_mfma_f32_32x32x16_bf16 v[96:111], v[170:173], v[138:141], v[96:111]
	v_add_f32_e32 v84, v80, v84
	v_exp_f32_e32 v75, v86
	v_add_f32_e32 v84, v73, v84
	v_exp_f32_e32 v83, v87
	v_add_f32_e32 v84, v81, v84
	v_exp_f32_e32 v76, v88
	v_add_f32_e32 v84, v74, v84
	v_mfma_f32_32x32x16_bf16 v[96:111], v[162:165], v[112:115], v[96:111]
	v_exp_f32_e32 v85, v89
	v_add_f32_e32 v84, v82, v84
	v_exp_f32_e32 v77, v90
	v_add_f32_e32 v84, v75, v84
	v_exp_f32_e32 v87, v91
	v_add_f32_e32 v84, v83, v84
	v_exp_f32_e32 v78, v92
	v_mfma_f32_32x32x16_bf16 v[96:111], v[166:169], v[116:119], v[96:111]
	v_add_f32_e32 v84, v76, v84
	v_exp_f32_e32 v89, v93
	v_add_f32_e32 v84, v85, v84
	v_exp_f32_e32 v79, v94
	v_add_f32_e32 v84, v77, v84
	v_exp_f32_e32 v90, v95
	v_add_f32_e32 v84, v87, v84
	v_mfma_f32_32x32x16_bf16 v[96:111], v[174:177], v[120:123], v[96:111]
	v_add_f32_e32 v84, v78, v84
	v_add_f32_e32 v84, v89, v84
	v_add_f32_e32 v84, v79, v84
	v_add_f32_e32 v84, v90, v84
	v_lshl_add_u32 v88, v247, 2, s2
	v_cvt_pk_bf16_f32 v72, v72, v80
	v_cvt_pk_bf16_f32 v73, v73, v81
	v_mfma_f32_32x32x16_bf16 v[96:111], v[178:181], v[124:127], v[96:111]
	v_cvt_pk_bf16_f32 v74, v74, v82
	v_cvt_pk_bf16_f32 v75, v75, v83
	v_cvt_pk_bf16_f32 v76, v76, v85
	v_cvt_pk_bf16_f32 v77, v77, v87
	v_cvt_pk_bf16_f32 v78, v78, v89
	v_cvt_pk_bf16_f32 v79, v79, v90
	s_nop 0
	v_permlane32_swap_b32_e32 v72, v74
	v_mfma_f32_32x32x16_bf16 v[96:111], v[182:185], v[130:133], v[96:111]
	v_permlane32_swap_b32_e32 v73, v75
	v_permlane32_swap_b32_e32 v76, v78
	v_permlane32_swap_b32_e32 v77, v79
	v_mfma_f32_32x32x16_bf16 v[96:111], v[186:189], v[134:137], v[96:111]
	s_nop 11
	v_exp_f32_e32 v91, v96
	v_exp_f32_e32 v92, v97
	v_exp_f32_e32 v93, v98
	v_exp_f32_e32 v94, v99
	v_exp_f32_e32 v95, v100
	v_add_f32_e32 v84, v84, v91
	v_exp_f32_e32 v96, v101
	v_add_f32_e32 v84, v92, v84
	v_exp_f32_e32 v97, v102
	v_add_f32_e32 v84, v93, v84
	v_exp_f32_e32 v98, v103
	v_add_f32_e32 v84, v94, v84
	v_exp_f32_e32 v99, v104
	v_add_f32_e32 v84, v95, v84
	v_exp_f32_e32 v100, v105
	v_add_f32_e32 v84, v96, v84
	v_exp_f32_e32 v101, v106
	v_add_f32_e32 v84, v97, v84
	v_exp_f32_e32 v102, v107
	v_add_f32_e32 v84, v98, v84
	v_exp_f32_e32 v103, v108
	v_add_f32_e32 v84, v99, v84
	v_exp_f32_e32 v104, v109
	v_add_f32_e32 v84, v100, v84
	v_exp_f32_e32 v105, v110
	v_add_f32_e32 v84, v101, v84
	v_exp_f32_e32 v106, v111
	v_add_f32_e32 v84, v102, v84
	v_add_f32_e32 v84, v103, v84
	v_add_f32_e32 v84, v104, v84
	v_add_f32_e32 v84, v105, v84
	v_add_f32_e32 v84, v106, v84
	v_mov_b32_e32 v86, v84
	s_nop 1
	v_permlane32_swap_b32_e32 v84, v86
	v_cvt_pk_bf16_f32 v80, v91, v92
	v_cvt_pk_bf16_f32 v81, v93, v94
	v_cvt_pk_bf16_f32 v82, v95, v96
	v_cvt_pk_bf16_f32 v83, v97, v98
	v_cvt_pk_bf16_f32 v90, v99, v100
	v_cvt_pk_bf16_f32 v91, v101, v102
	v_cvt_pk_bf16_f32 v92, v103, v104
	v_cvt_pk_bf16_f32 v93, v105, v106
	s_nop 0
	v_permlane32_swap_b32_e32 v80, v82
	v_permlane32_swap_b32_e32 v81, v83
	v_permlane32_swap_b32_e32 v90, v92
	v_permlane32_swap_b32_e32 v91, v93
	ds_read_b64_tr_b16 v[94:95], v206 offset:0x4000
	ds_read_b64_tr_b16 v[96:97], v206 offset:0x4800
	ds_read_b64_tr_b16 v[98:99], v206 offset:0x5000
	ds_read_b64_tr_b16 v[100:101], v206 offset:0x5800
	ds_read_b64_tr_b16 v[102:103], v206 offset:0x6000
	ds_read_b64_tr_b16 v[104:105], v206 offset:0x6800
	ds_read_b64_tr_b16 v[106:107], v206 offset:0x7000
	ds_read_b64_tr_b16 v[108:109], v206 offset:0x7800
	s_waitcnt lgkmcnt(0)
; #define SBAR() __builtin_amdgcn_sched_barrier(0)
; __device__ __forceinline__ int crow(int r, int hi) { return (r & 3) + 8 * (r >> 2) + 4 * hi; }
; #define NOP_() do { } while (0)
; template <bool PARTIAL, bool FIXED> ...
;     ...
;   HALF_A(2, 1, do { if (mask_last) { asm volatile("; masked tail tile" ::: "memory"); const float NEG = -INFINITY; \
;       _Pragma("unroll") for (int r = 8; r < 16; ++r) pA0[r] = NEG; _Pragma("unroll") for (int r = 0; r < 16; ++r) pA1[r] = NEG; } } while (0), NOP_(), NOP_());
;     ...
;   SBAR(); finishSM(pA0, pA1, alA, l_reg, pa0, pa1, pa2, pa3); SBAR();
;   pv_i<2 * 16384>(o, vbi, pa0, pa1, pa2, pa3);
;     ...
;   if (PARTIAL) {
;     if (wid < 2) { float* po = PO + (wid * QBLK) * 128;
; #pragma unroll
;       for (int r = 0; r < 16; ++r) { const int orow = crow(r, hi);
; #pragma unroll
;         for (int d0 = 0; d0 < 4; ++d0) po[orow * 128 + d0 * 32 + r32] = o[d0][r]; }
;       if (hi == 0) { PO[8192 + (wid * QBLK + r32) * 2] = m_reg; PO[8192 + (wid * QBLK + r32) * 2 + 1] = l_reg; } }
;     __syncthreads();
;     return;
;   }
;   if (hi == 0) li_l[r32] = l_reg; asm volatile("s_waitcnt lgkmcnt(0)" ::: "memory");
	s_nop 0
	v_mfma_f32_32x32x16_bf16 v[0:15], v[72:75], v[94:97], v[0:15]
	ds_read_b64_tr_b16 v[94:95], v206 offset:0x4200
	ds_read_b64_tr_b16 v[96:97], v206 offset:0x4a00
	v_mfma_f32_32x32x16_bf16 v[0:15], v[76:79], v[98:101], v[0:15]
	ds_read_b64_tr_b16 v[98:99], v206 offset:0x5200
	ds_read_b64_tr_b16 v[100:101], v206 offset:0x5a00
	v_mfma_f32_32x32x16_bf16 v[0:15], v[80:83], v[102:105], v[0:15]
	ds_read_b64_tr_b16 v[102:103], v206 offset:0x6200
	ds_read_b64_tr_b16 v[104:105], v206 offset:0x6a00
	v_mfma_f32_32x32x16_bf16 v[0:15], v[90:93], v[106:109], v[0:15]
	ds_read_b64_tr_b16 v[106:107], v206 offset:0x7200
	ds_read_b64_tr_b16 v[108:109], v206 offset:0x7a00
	s_waitcnt lgkmcnt(0)
	v_mfma_f32_32x32x16_bf16 v[16:31], v[72:75], v[94:97], v[16:31]
	ds_read_b64_tr_b16 v[94:95], v206 offset:0x4400
	ds_read_b64_tr_b16 v[96:97], v206 offset:0x4c00
	v_mfma_f32_32x32x16_bf16 v[16:31], v[76:79], v[98:101], v[16:31]
	ds_read_b64_tr_b16 v[98:99], v206 offset:0x5400
	ds_read_b64_tr_b16 v[100:101], v206 offset:0x5c00
	v_mfma_f32_32x32x16_bf16 v[16:31], v[80:83], v[102:105], v[16:31]
	ds_read_b64_tr_b16 v[102:103], v206 offset:0x6400
	ds_read_b64_tr_b16 v[104:105], v206 offset:0x6c00
	v_mfma_f32_32x32x16_bf16 v[16:31], v[90:93], v[106:109], v[16:31]
	ds_read_b64_tr_b16 v[106:107], v206 offset:0x7400
	ds_read_b64_tr_b16 v[108:109], v206 offset:0x7c00
	s_waitcnt lgkmcnt(0)
	v_mfma_f32_32x32x16_bf16 v[32:47], v[72:75], v[94:97], v[32:47]
	ds_read_b64_tr_b16 v[94:95], v206 offset:0x4600
	ds_read_b64_tr_b16 v[96:97], v206 offset:0x4e00
	v_mfma_f32_32x32x16_bf16 v[32:47], v[76:79], v[98:101], v[32:47]
	ds_read_b64_tr_b16 v[98:99], v206 offset:0x5600
	ds_read_b64_tr_b16 v[100:101], v206 offset:0x5e00
	v_mfma_f32_32x32x16_bf16 v[32:47], v[80:83], v[102:105], v[32:47]
	ds_read_b64_tr_b16 v[102:103], v206 offset:0x6600
	ds_read_b64_tr_b16 v[104:105], v206 offset:0x6e00
	v_mfma_f32_32x32x16_bf16 v[32:47], v[90:93], v[106:109], v[32:47]
	ds_read_b64_tr_b16 v[106:107], v206 offset:0x7600
	ds_read_b64_tr_b16 v[108:109], v206 offset:0x7e00
	s_waitcnt lgkmcnt(0)
	v_mfma_f32_32x32x16_bf16 v[48:63], v[72:75], v[94:97], v[48:63]
	v_exp_f32_e32 v64, v64
	v_exp_f32_e32 v65, v65
	v_exp_f32_e32 v66, v66
	v_exp_f32_e32 v67, v67
	v_exp_f32_e32 v68, v68
	v_exp_f32_e32 v69, v69
	v_exp_f32_e32 v70, v70
	v_mfma_f32_32x32x16_bf16 v[48:63], v[76:79], v[98:101], v[48:63]
	v_exp_f32_e32 v71, v71
	v_mfma_f32_32x32x16_bf16 v[48:63], v[80:83], v[102:105], v[48:63]
	v_mfma_f32_32x32x16_bf16 v[48:63], v[90:93], v[106:109], v[48:63]
	v_add_f32_e32 v72, 0, v64
	v_add_f32_e32 v72, v65, v72
	v_add_f32_e32 v72, v66, v72
	v_add_f32_e32 v72, v67, v72
	v_add_f32_e32 v72, v68, v72
	v_add_f32_e32 v72, v69, v72
	v_add_f32_e32 v72, v70, v72
	v_add_f32_e32 v72, v71, v72
	v_add_f32_e32 v85, 0, v72
	v_mov_b32_e32 v87, v85
	s_nop 1
	v_permlane32_swap_b32_e32 v85, v87
	v_cvt_pk_bf16_f32 v64, v64, v65
	v_cvt_pk_bf16_f32 v65, v66, v67
	v_cvt_pk_bf16_f32 v66, v68, v69
	v_cvt_pk_bf16_f32 v67, v70, v71
	v_cvt_pk_bf16_f32 v68, v129, v129
	v_cvt_pk_bf16_f32 v69, v129, v129
	v_cvt_pk_bf16_f32 v70, v129, v129
	v_cvt_pk_bf16_f32 v71, v129, v129
	v_cvt_pk_bf16_f32 v72, v129, v129
	v_cvt_pk_bf16_f32 v73, v129, v129
	v_cvt_pk_bf16_f32 v74, v129, v129
	v_cvt_pk_bf16_f32 v75, v129, v129
	v_cvt_pk_bf16_f32 v76, v129, v129
	v_cvt_pk_bf16_f32 v77, v129, v129
	v_cvt_pk_bf16_f32 v78, v129, v129
	v_cvt_pk_bf16_f32 v79, v129, v129
	s_nop 0
	v_permlane32_swap_b32_e32 v64, v66
	v_permlane32_swap_b32_e32 v65, v67
	v_permlane32_swap_b32_e32 v68, v70
	v_permlane32_swap_b32_e32 v69, v71
	v_permlane32_swap_b32_e32 v72, v74
	v_permlane32_swap_b32_e32 v73, v75
	v_permlane32_swap_b32_e32 v76, v78
	v_permlane32_swap_b32_e32 v77, v79
	ds_read_b64_tr_b16 v[80:81], v206 offset:0x8000
	ds_read_b64_tr_b16 v[82:83], v206 offset:0x8800
	ds_read_b64_tr_b16 v[90:91], v206 offset:0x9000
	ds_read_b64_tr_b16 v[92:93], v206 offset:0x9800
	ds_read_b64_tr_b16 v[94:95], v206 offset:0xa000
	ds_read_b64_tr_b16 v[96:97], v206 offset:0xa800
	ds_read_b64_tr_b16 v[98:99], v206 offset:0xb000
	ds_read_b64_tr_b16 v[100:101], v206 offset:0xb800
	s_waitcnt lgkmcnt(0)
	s_nop 0
	v_mfma_f32_32x32x16_bf16 v[0:15], v[64:67], v[80:83], v[0:15]
	ds_read_b64_tr_b16 v[80:81], v206 offset:0x8200
	ds_read_b64_tr_b16 v[82:83], v206 offset:0x8a00
	v_mfma_f32_32x32x16_bf16 v[0:15], v[68:71], v[90:93], v[0:15]
	ds_read_b64_tr_b16 v[90:91], v206 offset:0x9200
	ds_read_b64_tr_b16 v[92:93], v206 offset:0x9a00
	v_mfma_f32_32x32x16_bf16 v[0:15], v[72:75], v[94:97], v[0:15]
	ds_read_b64_tr_b16 v[94:95], v206 offset:0xa200
	ds_read_b64_tr_b16 v[96:97], v206 offset:0xaa00
	v_mfma_f32_32x32x16_bf16 v[0:15], v[76:79], v[98:101], v[0:15]
	ds_read_b64_tr_b16 v[98:99], v206 offset:0xb200
	ds_read_b64_tr_b16 v[100:101], v206 offset:0xba00
	s_waitcnt lgkmcnt(0)
	v_mfma_f32_32x32x16_bf16 v[16:31], v[64:67], v[80:83], v[16:31]
	ds_read_b64_tr_b16 v[80:81], v206 offset:0x8400
	ds_read_b64_tr_b16 v[82:83], v206 offset:0x8c00
	v_mfma_f32_32x32x16_bf16 v[16:31], v[68:71], v[90:93], v[16:31]
	ds_read_b64_tr_b16 v[90:91], v206 offset:0x9400
	ds_read_b64_tr_b16 v[92:93], v206 offset:0x9c00
	v_mfma_f32_32x32x16_bf16 v[16:31], v[72:75], v[94:97], v[16:31]
	ds_read_b64_tr_b16 v[94:95], v206 offset:0xa400
	ds_read_b64_tr_b16 v[96:97], v206 offset:0xac00
	v_mfma_f32_32x32x16_bf16 v[16:31], v[76:79], v[98:101], v[16:31]
	ds_read_b64_tr_b16 v[98:99], v206 offset:0xb400
	ds_read_b64_tr_b16 v[100:101], v206 offset:0xbc00
	s_waitcnt lgkmcnt(0)
	v_mfma_f32_32x32x16_bf16 v[32:47], v[64:67], v[80:83], v[32:47]
	ds_read_b64_tr_b16 v[80:81], v206 offset:0x8600
	ds_read_b64_tr_b16 v[82:83], v206 offset:0x8e00
	v_mfma_f32_32x32x16_bf16 v[32:47], v[68:71], v[90:93], v[32:47]
	ds_read_b64_tr_b16 v[90:91], v206 offset:0x9600
	ds_read_b64_tr_b16 v[92:93], v206 offset:0x9e00
	v_mfma_f32_32x32x16_bf16 v[32:47], v[72:75], v[94:97], v[32:47]
	ds_read_b64_tr_b16 v[94:95], v206 offset:0xa600
	ds_read_b64_tr_b16 v[96:97], v206 offset:0xae00
	v_mfma_f32_32x32x16_bf16 v[32:47], v[76:79], v[98:101], v[32:47]
	ds_read_b64_tr_b16 v[98:99], v206 offset:0xb600
	ds_read_b64_tr_b16 v[100:101], v206 offset:0xbe00
	s_waitcnt lgkmcnt(0)
	v_mfma_f32_32x32x16_bf16 v[48:63], v[64:67], v[80:83], v[48:63]
	v_cmp_gt_u32_e32 vcc, 32, v190
	v_mfma_f32_32x32x16_bf16 v[48:63], v[68:71], v[90:93], v[48:63]
	v_mfma_f32_32x32x16_bf16 v[48:63], v[72:75], v[94:97], v[48:63]
	v_mfma_f32_32x32x16_bf16 v[48:63], v[76:79], v[98:101], v[48:63]
	s_and_saveexec_b64 s[28:29], vcc
	s_cbranch_execz .LBB0_309
	v_add_f32_e32 v64, v128, v218
	v_add_f32_e32 v66, v215, v64
	v_pk_add_f32 v[64:65], v[84:85], v[86:87]
	v_lshl_add_u32 v67, v192, 2, v88
	v_add_f32_e32 v64, v66, v64
	v_add_f32_e32 v64, v64, v65
	ds_write_b32 v67, v64
	s_branch .LBB0_309
